# bf16 GEMM main loops: MFMAs of each MMA block re-ordered so both k-steps of an accumulator issue back to back (accumulate chain), snake over the 4x2 tile grid; bit-identical math
# speedup vs baseline: 1.0114x; 1.0076x over previous
.LBB0_166:
	s_add_u32 s42, s2, 0x10000
	s_waitcnt lgkmcnt(0)
	s_addc_u32 s43, s3, 0
	s_add_u32 s52, s48, 0x10000
	s_addc_u32 s53, s49, 0
	s_barrier
	s_setprio 1
	s_waitcnt lgkmcnt(7)
	s_waitcnt lgkmcnt(0)
	v_mfma_f32_16x16x32_bf16 v[32:35], v[16:19], v[76:79], 0
	v_mfma_f32_16x16x32_bf16 v[32:35], v[20:23], v[84:87], v[32:35]
	v_mfma_f32_16x16x32_bf16 v[36:39], v[24:27], v[76:79], 0
	v_mfma_f32_16x16x32_bf16 v[36:39], v[28:31], v[84:87], v[36:39]
	v_mfma_f32_16x16x32_bf16 v[44:47], v[24:27], v[92:95], 0
	v_mfma_f32_16x16x32_bf16 v[44:47], v[28:31], v[96:99], v[44:47]
	v_mfma_f32_16x16x32_bf16 v[40:43], v[16:19], v[92:95], 0
	v_mfma_f32_16x16x32_bf16 v[40:43], v[20:23], v[96:99], v[40:43]
	v_mfma_f32_16x16x32_bf16 v[48:51], v[16:19], v[80:83], 0
	v_mfma_f32_16x16x32_bf16 v[48:51], v[20:23], v[88:91], v[48:51]
	v_mfma_f32_16x16x32_bf16 v[52:55], v[24:27], v[80:83], 0
	v_mfma_f32_16x16x32_bf16 v[52:55], v[28:31], v[88:91], v[52:55]
	v_mfma_f32_16x16x32_bf16 v[64:67], v[24:27], v[60:63], 0
	v_mfma_f32_16x16x32_bf16 v[64:67], v[28:31], v[72:75], v[64:67]
	v_mfma_f32_16x16x32_bf16 v[56:59], v[16:19], v[60:63], 0
	v_mfma_f32_16x16x32_bf16 v[56:59], v[20:23], v[72:75], v[56:59]
	s_setprio 0
	s_setprio 1
	v_mfma_f32_16x16x32_bf16 v[68:71], v[0:3], v[76:79], 0
	v_mfma_f32_16x16x32_bf16 v[76:79], v[8:11], v[76:79], 0
	v_mfma_f32_16x16x32_bf16 v[68:71], v[4:7], v[84:87], v[68:71]
	v_mfma_f32_16x16x32_bf16 v[76:79], v[12:15], v[84:87], v[76:79]
	v_mfma_f32_16x16x32_bf16 v[84:87], v[0:3], v[92:95], 0
	v_mfma_f32_16x16x32_bf16 v[92:95], v[8:11], v[92:95], 0
	v_mfma_f32_16x16x32_bf16 v[84:87], v[4:7], v[96:99], v[84:87]
	v_mfma_f32_16x16x32_bf16 v[92:95], v[12:15], v[96:99], v[92:95]
	v_mfma_f32_16x16x32_bf16 v[96:99], v[0:3], v[80:83], 0
	v_mfma_f32_16x16x32_bf16 v[80:83], v[8:11], v[80:83], 0
	v_mfma_f32_16x16x32_bf16 v[132:135], v[12:15], v[88:91], v[80:83]
	v_mfma_f32_16x16x32_bf16 v[80:83], v[0:3], v[60:63], 0
	v_mfma_f32_16x16x32_bf16 v[60:63], v[8:11], v[60:63], 0
	v_mfma_f32_16x16x32_bf16 v[128:131], v[4:7], v[88:91], v[96:99]
	v_mfma_f32_16x16x32_bf16 v[136:139], v[4:7], v[72:75], v[80:83]
	v_mfma_f32_16x16x32_bf16 v[140:143], v[12:15], v[72:75], v[60:63]
	s_setprio 0
	s_barrier
	ds_read_b128 v[104:107], v170 offset:16384
	ds_read_b128 v[108:111], v170 offset:17408
	ds_read_b128 v[96:99], v170 offset:18432
	ds_read_b128 v[100:103], v170 offset:19456
	ds_read_b128 v[80:83], v170 offset:20480
	ds_read_b128 v[88:91], v170 offset:21504
	ds_read_b128 v[60:63], v170 offset:22528
	ds_read_b128 v[72:75], v170 offset:23552
	s_mov_b32 m0, s45
	s_nop 0
	global_load_lds_dwordx4 v166, s[52:53]
	s_add_u32 s52, s48, 0x12000
	s_addc_u32 s53, s49, 0
	s_mov_b32 m0, s47
	s_nop 0
	global_load_lds_dwordx4 v166, s[52:53]
	s_add_u32 s52, s48, 0x14000
	s_addc_u32 s53, s49, 0
	s_mov_b32 m0, s58
	s_nop 0
	global_load_lds_dwordx4 v166, s[52:53]
	s_add_u32 s52, s48, 0x16000
	s_addc_u32 s53, s49, 0
	s_mov_b32 m0, s59
	s_nop 0
	global_load_lds_dwordx4 v166, s[52:53]
	s_nop 0
	s_mov_b32 m0, s57
	s_nop 0
	global_load_lds_dwordx4 v166, s[42:43]
	s_add_u32 s42, s2, 0x12000
	s_addc_u32 s43, s3, 0
	s_mov_b32 m0, s60
	s_nop 0
	global_load_lds_dwordx4 v166, s[42:43]
	s_and_b64 vcc, exec, s[40:41]
	s_cbranch_vccz .LBB0_177
	s_waitcnt vmcnt(16)
	s_cbranch_execnz .LBB0_169

.LBB0_170:
	ds_read_b128 v[128:131], v168
	ds_read_b128 v[132:135], v168 offset:1024
	ds_read_b128 v[136:139], v168 offset:2048
	ds_read_b128 v[140:143], v168 offset:3072
	ds_read_b128 v[152:155], v169
	ds_read_b128 v[156:159], v169 offset:1024
	ds_read_b128 v[160:163], v169 offset:2048
	ds_read_b128 v[172:175], v169 offset:3072
	s_add_u32 s2, s52, 0x10000
	s_addc_u32 s3, s53, 0
	s_cmp_eq_u32 s88, 60
	s_cselect_b32 s48, s82, s2
	s_cselect_b32 s49, s39, s3
	s_cselect_b32 s90, s83, s54
	s_cselect_b32 s91, s15, s55
	s_add_u32 s80, s48, 0x8000
	s_addc_u32 s81, s49, 0
	ds_read_b128 v[176:179], v170
	ds_read_b128 v[180:183], v170 offset:1024
	ds_read_b128 v[184:187], v170 offset:2048
	ds_read_b128 v[188:191], v170 offset:3072
	ds_read_b128 v[192:195], v170 offset:4096
	ds_read_b128 v[196:199], v170 offset:5120
	ds_read_b128 v[200:203], v170 offset:6144
	ds_read_b128 v[204:207], v170 offset:7168
	s_add_u32 s92, s52, 0xc000
	s_addc_u32 s93, s53, 0
	s_mov_b32 m0, s72
	s_nop 0
	global_load_lds_dwordx4 v166, s[92:93]
	s_add_u32 s52, s52, 0xe000
	s_addc_u32 s53, s53, 0
	s_mov_b32 m0, s75
	s_nop 0
	global_load_lds_dwordx4 v166, s[52:53]
	s_waitcnt vmcnt(8)
	s_waitcnt lgkmcnt(0)
	s_add_u32 s92, s90, 0x8000
	s_addc_u32 s93, s91, 0
	s_barrier
	s_setprio 1
	s_waitcnt lgkmcnt(7)
	s_waitcnt lgkmcnt(0)
	v_mfma_f32_16x16x32_bf16 v[112:115], v[128:131], v[176:179], v[112:115]
	v_mfma_f32_16x16x32_bf16 v[112:115], v[132:135], v[180:183], v[112:115]
	v_mfma_f32_16x16x32_bf16 v[120:123], v[136:139], v[176:179], v[120:123]
	v_mfma_f32_16x16x32_bf16 v[120:123], v[140:143], v[180:183], v[120:123]
	v_mfma_f32_16x16x32_bf16 v[104:107], v[136:139], v[184:187], v[104:107]
	v_mfma_f32_16x16x32_bf16 v[104:107], v[140:143], v[188:191], v[104:107]
	v_mfma_f32_16x16x32_bf16 v[96:99], v[128:131], v[184:187], v[96:99]
	v_mfma_f32_16x16x32_bf16 v[96:99], v[132:135], v[188:191], v[96:99]
	v_mfma_f32_16x16x32_bf16 v[80:83], v[128:131], v[192:195], v[80:83]
	v_mfma_f32_16x16x32_bf16 v[80:83], v[132:135], v[196:199], v[80:83]
	v_mfma_f32_16x16x32_bf16 v[88:91], v[136:139], v[192:195], v[88:91]
	v_mfma_f32_16x16x32_bf16 v[88:91], v[140:143], v[196:199], v[88:91]
	v_mfma_f32_16x16x32_bf16 v[72:75], v[136:139], v[200:203], v[72:75]
	v_mfma_f32_16x16x32_bf16 v[72:75], v[140:143], v[204:207], v[72:75]
	v_mfma_f32_16x16x32_bf16 v[60:63], v[128:131], v[200:203], v[60:63]
	v_mfma_f32_16x16x32_bf16 v[60:63], v[132:135], v[204:207], v[60:63]
	s_setprio 0
	s_setprio 1
	s_waitcnt lgkmcnt(0)
	v_mfma_f32_16x16x32_bf16 v[116:119], v[152:155], v[176:179], v[116:119]
	v_mfma_f32_16x16x32_bf16 v[116:119], v[156:159], v[180:183], v[116:119]
	v_mfma_f32_16x16x32_bf16 v[124:127], v[160:163], v[176:179], v[124:127]
	v_mfma_f32_16x16x32_bf16 v[124:127], v[172:175], v[180:183], v[124:127]
	v_mfma_f32_16x16x32_bf16 v[108:111], v[160:163], v[184:187], v[108:111]
	v_mfma_f32_16x16x32_bf16 v[108:111], v[172:175], v[188:191], v[108:111]
	v_mfma_f32_16x16x32_bf16 v[100:103], v[152:155], v[184:187], v[100:103]
	v_mfma_f32_16x16x32_bf16 v[100:103], v[156:159], v[188:191], v[100:103]
	v_mfma_f32_16x16x32_bf16 v[84:87], v[152:155], v[192:195], v[84:87]
	v_mfma_f32_16x16x32_bf16 v[84:87], v[156:159], v[196:199], v[84:87]
	v_mfma_f32_16x16x32_bf16 v[92:95], v[160:163], v[192:195], v[92:95]
	v_mfma_f32_16x16x32_bf16 v[92:95], v[172:175], v[196:199], v[92:95]
	v_mfma_f32_16x16x32_bf16 v[76:79], v[160:163], v[200:203], v[76:79]
	v_mfma_f32_16x16x32_bf16 v[76:79], v[172:175], v[204:207], v[76:79]
	v_mfma_f32_16x16x32_bf16 v[68:71], v[152:155], v[200:203], v[68:71]
	v_mfma_f32_16x16x32_bf16 v[68:71], v[156:159], v[204:207], v[68:71]
	s_setprio 0
	s_barrier
	s_add_u32 s52, s90, 0x2000
	ds_read_b128 v[176:179], v170 offset:16384
	ds_read_b128 v[180:183], v170 offset:17408
	ds_read_b128 v[184:187], v170 offset:18432
	ds_read_b128 v[188:191], v170 offset:19456
	ds_read_b128 v[192:195], v170 offset:20480
	ds_read_b128 v[196:199], v170 offset:21504
	ds_read_b128 v[200:203], v170 offset:22528
	ds_read_b128 v[204:207], v170 offset:23552
	s_mov_b32 m0, s45
	s_nop 0
	global_load_lds_dwordx4 v166, s[90:91]
	s_addc_u32 s53, s91, 0
	s_mov_b32 m0, s47
	s_nop 0
	global_load_lds_dwordx4 v166, s[52:53]
	s_add_u32 s52, s90, 0x4000
	s_addc_u32 s53, s91, 0
	s_mov_b32 m0, s58
	s_nop 0
	global_load_lds_dwordx4 v166, s[52:53]
	s_add_u32 s52, s90, 0x6000
	s_addc_u32 s53, s91, 0
	s_mov_b32 m0, s59
	s_nop 0
	global_load_lds_dwordx4 v166, s[52:53]
	s_add_u32 s52, s48, 0x2000
	s_mov_b32 m0, s57
	s_nop 0
	global_load_lds_dwordx4 v166, s[48:49]
	s_addc_u32 s53, s49, 0
	s_mov_b32 m0, s60
	s_nop 0
	global_load_lds_dwordx4 v166, s[52:53]
	s_waitcnt vmcnt(8)
	s_waitcnt lgkmcnt(0)
	s_barrier
	s_setprio 1
	s_waitcnt lgkmcnt(7)
	s_waitcnt lgkmcnt(0)
	v_mfma_f32_16x16x32_bf16 v[48:51], v[128:131], v[176:179], v[48:51]
	v_mfma_f32_16x16x32_bf16 v[48:51], v[132:135], v[180:183], v[48:51]
	v_mfma_f32_16x16x32_bf16 v[56:59], v[136:139], v[176:179], v[56:59]
	v_mfma_f32_16x16x32_bf16 v[56:59], v[140:143], v[180:183], v[56:59]
	v_mfma_f32_16x16x32_bf16 v[40:43], v[136:139], v[184:187], v[40:43]
	v_mfma_f32_16x16x32_bf16 v[40:43], v[140:143], v[188:191], v[40:43]
	v_mfma_f32_16x16x32_bf16 v[32:35], v[128:131], v[184:187], v[32:35]
	v_mfma_f32_16x16x32_bf16 v[32:35], v[132:135], v[188:191], v[32:35]
	v_mfma_f32_16x16x32_bf16 v[16:19], v[128:131], v[192:195], v[16:19]
	v_mfma_f32_16x16x32_bf16 v[16:19], v[132:135], v[196:199], v[16:19]
	v_mfma_f32_16x16x32_bf16 v[24:27], v[136:139], v[192:195], v[24:27]
	v_mfma_f32_16x16x32_bf16 v[24:27], v[140:143], v[196:199], v[24:27]
	v_mfma_f32_16x16x32_bf16 v[8:11], v[136:139], v[200:203], v[8:11]
	v_mfma_f32_16x16x32_bf16 v[8:11], v[140:143], v[204:207], v[8:11]
	v_mfma_f32_16x16x32_bf16 v[0:3], v[128:131], v[200:203], v[0:3]
	v_mfma_f32_16x16x32_bf16 v[0:3], v[132:135], v[204:207], v[0:3]
	s_setprio 0
	s_setprio 1
	s_waitcnt lgkmcnt(0)
	v_mfma_f32_16x16x32_bf16 v[52:55], v[152:155], v[176:179], v[52:55]
	v_mfma_f32_16x16x32_bf16 v[52:55], v[156:159], v[180:183], v[52:55]
	v_mfma_f32_16x16x32_bf16 v[64:67], v[160:163], v[176:179], v[64:67]
	v_mfma_f32_16x16x32_bf16 v[64:67], v[172:175], v[180:183], v[64:67]
	v_mfma_f32_16x16x32_bf16 v[44:47], v[160:163], v[184:187], v[44:47]
	v_mfma_f32_16x16x32_bf16 v[44:47], v[172:175], v[188:191], v[44:47]
	v_mfma_f32_16x16x32_bf16 v[36:39], v[152:155], v[184:187], v[36:39]
	v_mfma_f32_16x16x32_bf16 v[36:39], v[156:159], v[188:191], v[36:39]
	v_mfma_f32_16x16x32_bf16 v[20:23], v[152:155], v[192:195], v[20:23]
	v_mfma_f32_16x16x32_bf16 v[20:23], v[156:159], v[196:199], v[20:23]
	v_mfma_f32_16x16x32_bf16 v[28:31], v[160:163], v[192:195], v[28:31]
	v_mfma_f32_16x16x32_bf16 v[28:31], v[172:175], v[196:199], v[28:31]
	v_mfma_f32_16x16x32_bf16 v[12:15], v[160:163], v[200:203], v[12:15]
	v_mfma_f32_16x16x32_bf16 v[12:15], v[172:175], v[204:207], v[12:15]
	v_mfma_f32_16x16x32_bf16 v[4:7], v[152:155], v[200:203], v[4:7]
	v_mfma_f32_16x16x32_bf16 v[4:7], v[156:159], v[204:207], v[4:7]
	s_setprio 0
	s_barrier
	ds_read_b128 v[128:131], v148
	ds_read_b128 v[132:135], v148 offset:1024
	ds_read_b128 v[136:139], v148 offset:2048
	ds_read_b128 v[140:143], v148 offset:3072
	ds_read_b128 v[152:155], v150
	ds_read_b128 v[156:159], v150 offset:1024
	ds_read_b128 v[160:163], v150 offset:2048
	ds_read_b128 v[172:175], v150 offset:3072
	ds_read_b128 v[176:179], v170 offset:32768
	ds_read_b128 v[180:183], v170 offset:33792
	ds_read_b128 v[184:187], v170 offset:34816
	ds_read_b128 v[188:191], v170 offset:35840
	ds_read_b128 v[192:195], v170 offset:36864
	ds_read_b128 v[196:199], v170 offset:37888
	ds_read_b128 v[200:203], v170 offset:38912
	ds_read_b128 v[204:207], v170 offset:39936
	s_add_u32 s52, s48, 0x4000
	s_addc_u32 s53, s49, 0
	s_mov_b32 m0, s61
	s_nop 0
	global_load_lds_dwordx4 v166, s[52:53]
	s_add_u32 s52, s48, 0x6000
	s_addc_u32 s53, s49, 0
	s_mov_b32 m0, s62
	s_nop 0
	global_load_lds_dwordx4 v166, s[52:53]
	s_waitcnt vmcnt(8)
	s_waitcnt lgkmcnt(0)
	s_barrier
	s_setprio 1
	s_waitcnt lgkmcnt(7)
	s_waitcnt lgkmcnt(0)
	v_mfma_f32_16x16x32_bf16 v[112:115], v[128:131], v[176:179], v[112:115]
	v_mfma_f32_16x16x32_bf16 v[112:115], v[132:135], v[180:183], v[112:115]
	v_mfma_f32_16x16x32_bf16 v[120:123], v[136:139], v[176:179], v[120:123]
	v_mfma_f32_16x16x32_bf16 v[120:123], v[140:143], v[180:183], v[120:123]
	v_mfma_f32_16x16x32_bf16 v[104:107], v[136:139], v[184:187], v[104:107]
	v_mfma_f32_16x16x32_bf16 v[104:107], v[140:143], v[188:191], v[104:107]
	v_mfma_f32_16x16x32_bf16 v[96:99], v[128:131], v[184:187], v[96:99]
	v_mfma_f32_16x16x32_bf16 v[96:99], v[132:135], v[188:191], v[96:99]
	v_mfma_f32_16x16x32_bf16 v[80:83], v[128:131], v[192:195], v[80:83]
	v_mfma_f32_16x16x32_bf16 v[80:83], v[132:135], v[196:199], v[80:83]
	v_mfma_f32_16x16x32_bf16 v[88:91], v[136:139], v[192:195], v[88:91]
	v_mfma_f32_16x16x32_bf16 v[88:91], v[140:143], v[196:199], v[88:91]
	v_mfma_f32_16x16x32_bf16 v[72:75], v[136:139], v[200:203], v[72:75]
	v_mfma_f32_16x16x32_bf16 v[72:75], v[140:143], v[204:207], v[72:75]
	v_mfma_f32_16x16x32_bf16 v[60:63], v[128:131], v[200:203], v[60:63]
	v_mfma_f32_16x16x32_bf16 v[60:63], v[132:135], v[204:207], v[60:63]
	s_setprio 0
	s_setprio 1
	s_waitcnt lgkmcnt(0)
	v_mfma_f32_16x16x32_bf16 v[116:119], v[152:155], v[176:179], v[116:119]
	v_mfma_f32_16x16x32_bf16 v[116:119], v[156:159], v[180:183], v[116:119]
	v_mfma_f32_16x16x32_bf16 v[124:127], v[160:163], v[176:179], v[124:127]
	v_mfma_f32_16x16x32_bf16 v[124:127], v[172:175], v[180:183], v[124:127]
	v_mfma_f32_16x16x32_bf16 v[108:111], v[160:163], v[184:187], v[108:111]
	v_mfma_f32_16x16x32_bf16 v[108:111], v[172:175], v[188:191], v[108:111]
	v_mfma_f32_16x16x32_bf16 v[100:103], v[152:155], v[184:187], v[100:103]
	v_mfma_f32_16x16x32_bf16 v[100:103], v[156:159], v[188:191], v[100:103]
	v_mfma_f32_16x16x32_bf16 v[84:87], v[152:155], v[192:195], v[84:87]
	v_mfma_f32_16x16x32_bf16 v[84:87], v[156:159], v[196:199], v[84:87]
	v_mfma_f32_16x16x32_bf16 v[92:95], v[160:163], v[192:195], v[92:95]
	v_mfma_f32_16x16x32_bf16 v[92:95], v[172:175], v[196:199], v[92:95]
	v_mfma_f32_16x16x32_bf16 v[76:79], v[160:163], v[200:203], v[76:79]
	v_mfma_f32_16x16x32_bf16 v[76:79], v[172:175], v[204:207], v[76:79]
	v_mfma_f32_16x16x32_bf16 v[68:71], v[152:155], v[200:203], v[68:71]
	v_mfma_f32_16x16x32_bf16 v[68:71], v[156:159], v[204:207], v[68:71]
	s_setprio 0
	s_barrier
	s_add_u32 s52, s90, 0xa000
	ds_read_b128 v[176:179], v170 offset:49152
	ds_read_b128 v[180:183], v170 offset:50176
	ds_read_b128 v[184:187], v170 offset:51200
	ds_read_b128 v[188:191], v170 offset:52224
	ds_read_b128 v[192:195], v170 offset:53248
	ds_read_b128 v[196:199], v170 offset:54272
	ds_read_b128 v[200:203], v170 offset:55296
	ds_read_b128 v[204:207], v170 offset:56320
	s_mov_b32 m0, s66
	s_nop 0
	global_load_lds_dwordx4 v166, s[92:93]
	s_addc_u32 s53, s91, 0
	s_mov_b32 m0, s67
	s_nop 0
	global_load_lds_dwordx4 v166, s[52:53]
	s_add_u32 s52, s90, 0xc000
	s_addc_u32 s53, s91, 0
	s_mov_b32 m0, s70
	s_nop 0
	global_load_lds_dwordx4 v166, s[52:53]
	s_add_u32 s52, s90, 0xe000
	s_addc_u32 s53, s91, 0
	s_mov_b32 m0, s71
	s_nop 0
	global_load_lds_dwordx4 v166, s[52:53]
	s_add_u32 s48, s48, 0xa000
	s_mov_b32 m0, s68
	s_nop 0
	global_load_lds_dwordx4 v166, s[80:81]
	s_addc_u32 s49, s49, 0
	s_mov_b32 m0, s69
	s_nop 0
	global_load_lds_dwordx4 v166, s[48:49]
	s_waitcnt vmcnt(8)
	s_waitcnt lgkmcnt(0)
	s_barrier
	s_setprio 1
	s_waitcnt lgkmcnt(7)
	s_waitcnt lgkmcnt(0)
	v_mfma_f32_16x16x32_bf16 v[48:51], v[128:131], v[176:179], v[48:51]
	v_mfma_f32_16x16x32_bf16 v[48:51], v[132:135], v[180:183], v[48:51]
	v_mfma_f32_16x16x32_bf16 v[56:59], v[136:139], v[176:179], v[56:59]
	v_mfma_f32_16x16x32_bf16 v[56:59], v[140:143], v[180:183], v[56:59]
	v_mfma_f32_16x16x32_bf16 v[40:43], v[136:139], v[184:187], v[40:43]
	v_mfma_f32_16x16x32_bf16 v[40:43], v[140:143], v[188:191], v[40:43]
	v_mfma_f32_16x16x32_bf16 v[32:35], v[128:131], v[184:187], v[32:35]
	v_mfma_f32_16x16x32_bf16 v[32:35], v[132:135], v[188:191], v[32:35]
	v_mfma_f32_16x16x32_bf16 v[16:19], v[128:131], v[192:195], v[16:19]
	v_mfma_f32_16x16x32_bf16 v[16:19], v[132:135], v[196:199], v[16:19]
	v_mfma_f32_16x16x32_bf16 v[24:27], v[136:139], v[192:195], v[24:27]
	v_mfma_f32_16x16x32_bf16 v[24:27], v[140:143], v[196:199], v[24:27]
	v_mfma_f32_16x16x32_bf16 v[8:11], v[136:139], v[200:203], v[8:11]
	v_mfma_f32_16x16x32_bf16 v[8:11], v[140:143], v[204:207], v[8:11]
	v_mfma_f32_16x16x32_bf16 v[0:3], v[128:131], v[200:203], v[0:3]
	v_mfma_f32_16x16x32_bf16 v[0:3], v[132:135], v[204:207], v[0:3]
	s_setprio 0
	s_setprio 1
	s_waitcnt lgkmcnt(0)
	v_mfma_f32_16x16x32_bf16 v[52:55], v[152:155], v[176:179], v[52:55]
	v_mfma_f32_16x16x32_bf16 v[52:55], v[156:159], v[180:183], v[52:55]
	v_mfma_f32_16x16x32_bf16 v[64:67], v[160:163], v[176:179], v[64:67]
	v_mfma_f32_16x16x32_bf16 v[64:67], v[172:175], v[180:183], v[64:67]
	v_mfma_f32_16x16x32_bf16 v[44:47], v[160:163], v[184:187], v[44:47]
	v_mfma_f32_16x16x32_bf16 v[44:47], v[172:175], v[188:191], v[44:47]
	v_mfma_f32_16x16x32_bf16 v[36:39], v[152:155], v[184:187], v[36:39]
	v_mfma_f32_16x16x32_bf16 v[36:39], v[156:159], v[188:191], v[36:39]
	v_mfma_f32_16x16x32_bf16 v[20:23], v[152:155], v[192:195], v[20:23]
	v_mfma_f32_16x16x32_bf16 v[20:23], v[156:159], v[196:199], v[20:23]
	v_mfma_f32_16x16x32_bf16 v[28:31], v[160:163], v[192:195], v[28:31]
	v_mfma_f32_16x16x32_bf16 v[28:31], v[172:175], v[196:199], v[28:31]
	v_mfma_f32_16x16x32_bf16 v[12:15], v[160:163], v[200:203], v[12:15]
	v_mfma_f32_16x16x32_bf16 v[12:15], v[172:175], v[204:207], v[12:15]
	v_mfma_f32_16x16x32_bf16 v[4:7], v[152:155], v[200:203], v[4:7]
	v_mfma_f32_16x16x32_bf16 v[4:7], v[156:159], v[204:207], v[4:7]
	s_setprio 0
	s_barrier
	s_add_i32 s88, s88, 2
	s_add_u32 s54, s54, 0x10000
	s_addc_u32 s55, s55, 0
	s_cmp_gt_u32 s88, 61
	s_mov_b64 s[52:53], s[2:3]
	s_cbranch_scc0 .LBB0_170
	s_and_b64 vcc, exec, s[12:13]
	s_cbranch_vccz .LBB0_173
	s_barrier

.LBB0_326:
	ds_read_b128 v[60:63], v212
	ds_read_b128 v[68:71], v212 offset:1024
	ds_read_b128 v[88:91], v212 offset:2048
	ds_read_b128 v[92:95], v212 offset:3072
	ds_read_b128 v[112:115], v213
	ds_read_b128 v[116:119], v213 offset:1024
	ds_read_b128 v[138:141], v213 offset:2048
	ds_read_b128 v[152:155], v213 offset:3072
	s_cmpk_eq_i32 s80, 0xa8
	s_cselect_b32 s2, s4, s76
	s_cselect_b32 s3, s5, s77
	s_cselect_b32 s42, s38, s78
	s_cselect_b32 s43, s39, s79
	s_add_u32 s40, s2, 0x8000
	s_addc_u32 s41, s3, 0
	ds_read_b128 v[164:167], v214
	ds_read_b128 v[168:171], v214 offset:1024
	ds_read_b128 v[172:175], v214 offset:2048
	ds_read_b128 v[176:179], v214 offset:3072
	ds_read_b128 v[180:183], v214 offset:4096
	ds_read_b128 v[184:187], v214 offset:5120
	ds_read_b128 v[188:191], v214 offset:6144
	ds_read_b128 v[192:195], v214 offset:7168
	s_add_u32 s44, s76, 0xffffc000
	s_addc_u32 s45, s77, -1
	s_mov_b32 m0, s65
	s_nop 0
	global_load_lds_dwordx4 v210, s[44:45]
	s_add_u32 s44, s76, 0xffffe000
	s_addc_u32 s45, s77, -1
	s_mov_b32 m0, s68
	s_nop 0
	global_load_lds_dwordx4 v210, s[44:45]
	s_waitcnt vmcnt(8)
	s_waitcnt lgkmcnt(0)
	s_add_u32 s44, s42, 0x8000
	s_addc_u32 s45, s43, 0
	s_barrier
	s_setprio 1
	s_waitcnt lgkmcnt(7)
	s_waitcnt lgkmcnt(0)
	v_mfma_f32_16x16x32_bf16 v[160:163], v[60:63], v[164:167], v[160:163]
	v_mfma_f32_16x16x32_bf16 v[160:163], v[68:71], v[168:171], v[160:163]
	v_mfma_f32_16x16x32_bf16 v[156:159], v[88:91], v[164:167], v[156:159]
	v_mfma_f32_16x16x32_bf16 v[156:159], v[92:95], v[168:171], v[156:159]
	v_mfma_f32_16x16x32_bf16 v[128:131], v[88:91], v[172:175], v[128:131]
	v_mfma_f32_16x16x32_bf16 v[128:131], v[92:95], v[176:179], v[128:131]
	v_mfma_f32_16x16x32_bf16 v[132:135], v[60:63], v[172:175], v[132:135]
	v_mfma_f32_16x16x32_bf16 v[132:135], v[68:71], v[176:179], v[132:135]
	v_mfma_f32_16x16x32_bf16 v[108:111], v[60:63], v[180:183], v[108:111]
	v_mfma_f32_16x16x32_bf16 v[108:111], v[68:71], v[184:187], v[108:111]
	v_mfma_f32_16x16x32_bf16 v[104:107], v[88:91], v[180:183], v[104:107]
	v_mfma_f32_16x16x32_bf16 v[104:107], v[92:95], v[184:187], v[104:107]
	v_mfma_f32_16x16x32_bf16 v[80:83], v[88:91], v[188:191], v[80:83]
	v_mfma_f32_16x16x32_bf16 v[80:83], v[92:95], v[192:195], v[80:83]
	v_mfma_f32_16x16x32_bf16 v[84:87], v[60:63], v[188:191], v[84:87]
	v_mfma_f32_16x16x32_bf16 v[84:87], v[68:71], v[192:195], v[84:87]
	s_setprio 0
	s_setprio 1
	v_mfma_f32_16x16x32_bf16 v[148:151], v[112:115], v[164:167], v[148:151]
	v_mfma_f32_16x16x32_bf16 v[142:145], v[138:141], v[164:167], v[144:147]
	v_mfma_f32_16x16x32_bf16 v[124:127], v[112:115], v[172:175], v[124:127]
	v_mfma_f32_16x16x32_bf16 v[120:123], v[138:141], v[172:175], v[120:123]
	v_mfma_f32_16x16x32_bf16 v[100:103], v[112:115], v[180:183], v[100:103]
	v_mfma_f32_16x16x32_bf16 v[96:99], v[138:141], v[180:183], v[96:99]
	v_mfma_f32_16x16x32_bf16 v[76:79], v[112:115], v[188:191], v[76:79]
	v_mfma_f32_16x16x32_bf16 v[72:75], v[138:141], v[188:191], v[72:75]
	v_mfma_f32_16x16x32_bf16 v[148:151], v[116:119], v[168:171], v[148:151]
	v_mfma_f32_16x16x32_bf16 v[142:145], v[152:155], v[168:171], v[142:145]
	v_mfma_f32_16x16x32_bf16 v[124:127], v[116:119], v[176:179], v[124:127]
	v_mfma_f32_16x16x32_bf16 v[120:123], v[152:155], v[176:179], v[120:123]
	v_mfma_f32_16x16x32_bf16 v[100:103], v[116:119], v[184:187], v[100:103]
	v_mfma_f32_16x16x32_bf16 v[96:99], v[152:155], v[184:187], v[96:99]
	v_mfma_f32_16x16x32_bf16 v[76:79], v[116:119], v[192:195], v[76:79]
	v_mfma_f32_16x16x32_bf16 v[72:75], v[152:155], v[192:195], v[72:75]
	s_setprio 0
	s_barrier
	s_add_u32 s82, s42, 0x2000
	ds_read_b128 v[164:167], v214 offset:16384
	ds_read_b128 v[168:171], v214 offset:17408
	ds_read_b128 v[172:175], v214 offset:18432
	ds_read_b128 v[176:179], v214 offset:19456
	ds_read_b128 v[180:183], v214 offset:20480
	ds_read_b128 v[184:187], v214 offset:21504
	ds_read_b128 v[188:191], v214 offset:22528
	ds_read_b128 v[192:195], v214 offset:23552
	s_mov_b32 m0, s47
	s_nop 0
	global_load_lds_dwordx4 v210, s[42:43]
	s_addc_u32 s83, s43, 0
	s_mov_b32 m0, s48
	s_nop 0
	global_load_lds_dwordx4 v210, s[82:83]
	s_add_u32 s82, s42, 0x4000
	s_addc_u32 s83, s43, 0
	s_mov_b32 m0, s49
	s_nop 0
	global_load_lds_dwordx4 v210, s[82:83]
	s_add_u32 s82, s42, 0x6000
	s_addc_u32 s83, s43, 0
	s_mov_b32 m0, s52
	s_nop 0
	global_load_lds_dwordx4 v210, s[82:83]
	s_add_u32 s82, s2, 0x2000
	s_mov_b32 m0, s46
	s_nop 0
	global_load_lds_dwordx4 v210, s[2:3]
	s_addc_u32 s83, s3, 0
	s_mov_b32 m0, s53
	s_nop 0
	global_load_lds_dwordx4 v210, s[82:83]
	s_waitcnt vmcnt(8)
	s_waitcnt lgkmcnt(0)
	s_barrier
	s_setprio 1
	s_waitcnt lgkmcnt(7)
	s_waitcnt lgkmcnt(0)
	v_mfma_f32_16x16x32_bf16 v[64:67], v[60:63], v[164:167], v[64:67]
	v_mfma_f32_16x16x32_bf16 v[64:67], v[68:71], v[168:171], v[64:67]
	v_mfma_f32_16x16x32_bf16 v[56:59], v[88:91], v[164:167], v[56:59]
	v_mfma_f32_16x16x32_bf16 v[56:59], v[92:95], v[168:171], v[56:59]
	v_mfma_f32_16x16x32_bf16 v[40:43], v[88:91], v[172:175], v[40:43]
	v_mfma_f32_16x16x32_bf16 v[40:43], v[92:95], v[176:179], v[40:43]
	v_mfma_f32_16x16x32_bf16 v[44:47], v[60:63], v[172:175], v[44:47]
	v_mfma_f32_16x16x32_bf16 v[44:47], v[68:71], v[176:179], v[44:47]
	v_mfma_f32_16x16x32_bf16 v[28:31], v[60:63], v[180:183], v[28:31]
	v_mfma_f32_16x16x32_bf16 v[28:31], v[68:71], v[184:187], v[28:31]
	v_mfma_f32_16x16x32_bf16 v[24:27], v[88:91], v[180:183], v[24:27]
	v_mfma_f32_16x16x32_bf16 v[24:27], v[92:95], v[184:187], v[24:27]
	v_mfma_f32_16x16x32_bf16 v[8:11], v[88:91], v[188:191], v[8:11]
	v_mfma_f32_16x16x32_bf16 v[8:11], v[92:95], v[192:195], v[8:11]
	v_mfma_f32_16x16x32_bf16 v[12:15], v[60:63], v[188:191], v[12:15]
	v_mfma_f32_16x16x32_bf16 v[12:15], v[68:71], v[192:195], v[12:15]
	s_setprio 0
	s_setprio 1
	s_waitcnt lgkmcnt(0)
	v_mfma_f32_16x16x32_bf16 v[52:55], v[112:115], v[164:167], v[52:55]
	v_mfma_f32_16x16x32_bf16 v[52:55], v[116:119], v[168:171], v[52:55]
	v_mfma_f32_16x16x32_bf16 v[48:51], v[138:141], v[164:167], v[48:51]
	v_mfma_f32_16x16x32_bf16 v[48:51], v[152:155], v[168:171], v[48:51]
	v_mfma_f32_16x16x32_bf16 v[32:35], v[138:141], v[172:175], v[32:35]
	v_mfma_f32_16x16x32_bf16 v[32:35], v[152:155], v[176:179], v[32:35]
	v_mfma_f32_16x16x32_bf16 v[36:39], v[112:115], v[172:175], v[36:39]
	v_mfma_f32_16x16x32_bf16 v[36:39], v[116:119], v[176:179], v[36:39]
	v_mfma_f32_16x16x32_bf16 v[20:23], v[112:115], v[180:183], v[20:23]
	v_mfma_f32_16x16x32_bf16 v[20:23], v[116:119], v[184:187], v[20:23]
	v_mfma_f32_16x16x32_bf16 v[16:19], v[138:141], v[180:183], v[16:19]
	v_mfma_f32_16x16x32_bf16 v[16:19], v[152:155], v[184:187], v[16:19]
	v_mfma_f32_16x16x32_bf16 v[0:3], v[138:141], v[188:191], v[0:3]
	v_mfma_f32_16x16x32_bf16 v[0:3], v[152:155], v[192:195], v[0:3]
	v_mfma_f32_16x16x32_bf16 v[4:7], v[112:115], v[188:191], v[4:7]
	v_mfma_f32_16x16x32_bf16 v[4:7], v[116:119], v[192:195], v[4:7]
	s_setprio 0
	s_barrier
	ds_read_b128 v[60:63], v136
	ds_read_b128 v[68:71], v136 offset:1024
	ds_read_b128 v[88:91], v136 offset:2048
	ds_read_b128 v[92:95], v136 offset:3072
	ds_read_b128 v[112:115], v137
	ds_read_b128 v[116:119], v137 offset:1024
	ds_read_b128 v[138:141], v137 offset:2048
	ds_read_b128 v[152:155], v137 offset:3072
	ds_read_b128 v[164:167], v214 offset:32768
	ds_read_b128 v[168:171], v214 offset:33792
	ds_read_b128 v[172:175], v214 offset:34816
	ds_read_b128 v[176:179], v214 offset:35840
	ds_read_b128 v[180:183], v214 offset:36864
	ds_read_b128 v[184:187], v214 offset:37888
	ds_read_b128 v[188:191], v214 offset:38912
	ds_read_b128 v[192:195], v214 offset:39936
	s_add_u32 s82, s2, 0x4000
	s_addc_u32 s83, s3, 0
	s_mov_b32 m0, s54
	s_nop 0
	global_load_lds_dwordx4 v210, s[82:83]
	s_add_u32 s82, s2, 0x6000
	s_addc_u32 s83, s3, 0
	s_mov_b32 m0, s55
	s_nop 0
	global_load_lds_dwordx4 v210, s[82:83]
	s_waitcnt vmcnt(8)
	s_waitcnt lgkmcnt(0)
	s_barrier
	s_setprio 1
	s_waitcnt lgkmcnt(7)
	s_waitcnt lgkmcnt(0)
	v_mfma_f32_16x16x32_bf16 v[160:163], v[60:63], v[164:167], v[160:163]
	v_mfma_f32_16x16x32_bf16 v[160:163], v[68:71], v[168:171], v[160:163]
	v_mfma_f32_16x16x32_bf16 v[156:159], v[88:91], v[164:167], v[156:159]
	v_mfma_f32_16x16x32_bf16 v[156:159], v[92:95], v[168:171], v[156:159]
	v_mfma_f32_16x16x32_bf16 v[128:131], v[88:91], v[172:175], v[128:131]
	v_mfma_f32_16x16x32_bf16 v[128:131], v[92:95], v[176:179], v[128:131]
	v_mfma_f32_16x16x32_bf16 v[132:135], v[60:63], v[172:175], v[132:135]
	v_mfma_f32_16x16x32_bf16 v[132:135], v[68:71], v[176:179], v[132:135]
	v_mfma_f32_16x16x32_bf16 v[108:111], v[60:63], v[180:183], v[108:111]
	v_mfma_f32_16x16x32_bf16 v[108:111], v[68:71], v[184:187], v[108:111]
	v_mfma_f32_16x16x32_bf16 v[104:107], v[88:91], v[180:183], v[104:107]
	v_mfma_f32_16x16x32_bf16 v[104:107], v[92:95], v[184:187], v[104:107]
	v_mfma_f32_16x16x32_bf16 v[80:83], v[88:91], v[188:191], v[80:83]
	v_mfma_f32_16x16x32_bf16 v[80:83], v[92:95], v[192:195], v[80:83]
	v_mfma_f32_16x16x32_bf16 v[84:87], v[60:63], v[188:191], v[84:87]
	v_mfma_f32_16x16x32_bf16 v[84:87], v[68:71], v[192:195], v[84:87]
	s_setprio 0
	s_setprio 1
	v_mfma_f32_16x16x32_bf16 v[146:149], v[112:115], v[164:167], v[148:151]
	v_mfma_f32_16x16x32_bf16 v[142:145], v[138:141], v[164:167], v[142:145]
	v_mfma_f32_16x16x32_bf16 v[124:127], v[112:115], v[172:175], v[124:127]
	v_mfma_f32_16x16x32_bf16 v[120:123], v[138:141], v[172:175], v[120:123]
	v_mfma_f32_16x16x32_bf16 v[100:103], v[112:115], v[180:183], v[100:103]
	v_mfma_f32_16x16x32_bf16 v[96:99], v[138:141], v[180:183], v[96:99]
	v_mfma_f32_16x16x32_bf16 v[76:79], v[112:115], v[188:191], v[76:79]
	v_mfma_f32_16x16x32_bf16 v[72:75], v[138:141], v[188:191], v[72:75]
	v_mfma_f32_16x16x32_bf16 v[148:151], v[116:119], v[168:171], v[146:149]
	v_mfma_f32_16x16x32_bf16 v[144:147], v[152:155], v[168:171], v[142:145]
	v_mfma_f32_16x16x32_bf16 v[124:127], v[116:119], v[176:179], v[124:127]
	v_mfma_f32_16x16x32_bf16 v[120:123], v[152:155], v[176:179], v[120:123]
	v_mfma_f32_16x16x32_bf16 v[100:103], v[116:119], v[184:187], v[100:103]
	v_mfma_f32_16x16x32_bf16 v[96:99], v[152:155], v[184:187], v[96:99]
	v_mfma_f32_16x16x32_bf16 v[76:79], v[116:119], v[192:195], v[76:79]
	v_mfma_f32_16x16x32_bf16 v[72:75], v[152:155], v[192:195], v[72:75]
	s_setprio 0
	s_barrier
	ds_read_b128 v[164:167], v214 offset:49152
	ds_read_b128 v[168:171], v214 offset:50176
	ds_read_b128 v[172:175], v214 offset:51200
	ds_read_b128 v[176:179], v214 offset:52224
	ds_read_b128 v[180:183], v214 offset:53248
	ds_read_b128 v[184:187], v214 offset:54272
	ds_read_b128 v[188:191], v214 offset:55296
	ds_read_b128 v[192:195], v214 offset:56320
	s_mov_b32 m0, s59
	s_nop 0
	global_load_lds_dwordx4 v210, s[44:45]
	s_add_u32 s44, s42, 0xa000
	s_addc_u32 s45, s43, 0
	s_mov_b32 m0, s60
	s_nop 0
	global_load_lds_dwordx4 v210, s[44:45]
	s_add_u32 s44, s42, 0xc000
	s_addc_u32 s45, s43, 0
	s_mov_b32 m0, s63
	s_nop 0
	global_load_lds_dwordx4 v210, s[44:45]
	s_add_u32 s42, s42, 0xe000
	s_addc_u32 s43, s43, 0
	s_mov_b32 m0, s64
	s_nop 0
	global_load_lds_dwordx4 v210, s[42:43]
	s_add_u32 s2, s2, 0xa000
	s_mov_b32 m0, s61
	s_nop 0
	global_load_lds_dwordx4 v210, s[40:41]
	s_addc_u32 s3, s3, 0
	s_mov_b32 m0, s62
	s_nop 0
	global_load_lds_dwordx4 v210, s[2:3]
	s_waitcnt vmcnt(8)
	s_waitcnt lgkmcnt(0)
	s_barrier
	s_setprio 1
	s_waitcnt lgkmcnt(7)
	s_waitcnt lgkmcnt(0)
	v_mfma_f32_16x16x32_bf16 v[64:67], v[60:63], v[164:167], v[64:67]
	v_mfma_f32_16x16x32_bf16 v[64:67], v[68:71], v[168:171], v[64:67]
	v_mfma_f32_16x16x32_bf16 v[56:59], v[88:91], v[164:167], v[56:59]
	v_mfma_f32_16x16x32_bf16 v[56:59], v[92:95], v[168:171], v[56:59]
	v_mfma_f32_16x16x32_bf16 v[40:43], v[88:91], v[172:175], v[40:43]
	v_mfma_f32_16x16x32_bf16 v[40:43], v[92:95], v[176:179], v[40:43]
	v_mfma_f32_16x16x32_bf16 v[44:47], v[60:63], v[172:175], v[44:47]
	v_mfma_f32_16x16x32_bf16 v[44:47], v[68:71], v[176:179], v[44:47]
	v_mfma_f32_16x16x32_bf16 v[28:31], v[60:63], v[180:183], v[28:31]
	v_mfma_f32_16x16x32_bf16 v[28:31], v[68:71], v[184:187], v[28:31]
	v_mfma_f32_16x16x32_bf16 v[24:27], v[88:91], v[180:183], v[24:27]
	v_mfma_f32_16x16x32_bf16 v[24:27], v[92:95], v[184:187], v[24:27]
	v_mfma_f32_16x16x32_bf16 v[8:11], v[88:91], v[188:191], v[8:11]
	v_mfma_f32_16x16x32_bf16 v[8:11], v[92:95], v[192:195], v[8:11]
	v_mfma_f32_16x16x32_bf16 v[12:15], v[60:63], v[188:191], v[12:15]
	v_mfma_f32_16x16x32_bf16 v[12:15], v[68:71], v[192:195], v[12:15]
	s_setprio 0
	s_setprio 1
	s_waitcnt lgkmcnt(0)
	v_mfma_f32_16x16x32_bf16 v[52:55], v[112:115], v[164:167], v[52:55]
	v_mfma_f32_16x16x32_bf16 v[52:55], v[116:119], v[168:171], v[52:55]
	v_mfma_f32_16x16x32_bf16 v[48:51], v[138:141], v[164:167], v[48:51]
	v_mfma_f32_16x16x32_bf16 v[48:51], v[152:155], v[168:171], v[48:51]
	v_mfma_f32_16x16x32_bf16 v[32:35], v[138:141], v[172:175], v[32:35]
	v_mfma_f32_16x16x32_bf16 v[32:35], v[152:155], v[176:179], v[32:35]
	v_mfma_f32_16x16x32_bf16 v[36:39], v[112:115], v[172:175], v[36:39]
	v_mfma_f32_16x16x32_bf16 v[36:39], v[116:119], v[176:179], v[36:39]
	v_mfma_f32_16x16x32_bf16 v[20:23], v[112:115], v[180:183], v[20:23]
	v_mfma_f32_16x16x32_bf16 v[20:23], v[116:119], v[184:187], v[20:23]
	v_mfma_f32_16x16x32_bf16 v[16:19], v[138:141], v[180:183], v[16:19]
	v_mfma_f32_16x16x32_bf16 v[16:19], v[152:155], v[184:187], v[16:19]
	v_mfma_f32_16x16x32_bf16 v[0:3], v[138:141], v[188:191], v[0:3]
	v_mfma_f32_16x16x32_bf16 v[0:3], v[152:155], v[192:195], v[0:3]
	v_mfma_f32_16x16x32_bf16 v[4:7], v[112:115], v[188:191], v[4:7]
	v_mfma_f32_16x16x32_bf16 v[4:7], v[116:119], v[192:195], v[4:7]
	s_setprio 0
	s_barrier
	s_add_i32 s80, s80, 2
	s_add_u32 s76, s76, 0x10000
	s_addc_u32 s77, s77, 0
	s_add_u32 s78, s78, 0x10000
	s_addc_u32 s79, s79, 0
	s_cmpk_gt_u32 s80, 0xa9
	s_cbranch_scc0 .LBB0_326
	s_and_b64 vcc, exec, s[12:13]
	s_cbranch_vccz .LBB0_329
	s_barrier

.LBB0_421:
	s_add_u32 s8, s48, 0x10000
	s_waitcnt lgkmcnt(0)
	s_addc_u32 s9, s49, 0
	s_add_u32 s52, s80, 0x10000
	s_addc_u32 s53, s81, 0
	s_barrier
	s_setprio 1
	s_waitcnt lgkmcnt(7)
	s_waitcnt lgkmcnt(0)
	v_mfma_f32_16x16x32_bf16 v[32:35], v[16:19], v[68:71], 0
	v_mfma_f32_16x16x32_bf16 v[32:35], v[20:23], v[80:83], v[32:35]
	v_mfma_f32_16x16x32_bf16 v[36:39], v[24:27], v[68:71], 0
	v_mfma_f32_16x16x32_bf16 v[36:39], v[28:31], v[80:83], v[36:39]
	v_mfma_f32_16x16x32_bf16 v[44:47], v[24:27], v[84:87], 0
	v_mfma_f32_16x16x32_bf16 v[44:47], v[28:31], v[96:99], v[44:47]
	v_mfma_f32_16x16x32_bf16 v[40:43], v[16:19], v[84:87], 0
	v_mfma_f32_16x16x32_bf16 v[40:43], v[20:23], v[96:99], v[40:43]
	v_mfma_f32_16x16x32_bf16 v[48:51], v[16:19], v[88:91], 0
	v_mfma_f32_16x16x32_bf16 v[48:51], v[20:23], v[92:95], v[48:51]
	v_mfma_f32_16x16x32_bf16 v[52:55], v[24:27], v[88:91], 0
	v_mfma_f32_16x16x32_bf16 v[52:55], v[28:31], v[92:95], v[52:55]
	v_mfma_f32_16x16x32_bf16 v[60:63], v[24:27], v[72:75], 0
	v_mfma_f32_16x16x32_bf16 v[60:63], v[28:31], v[76:79], v[60:63]
	v_mfma_f32_16x16x32_bf16 v[56:59], v[16:19], v[72:75], 0
	v_mfma_f32_16x16x32_bf16 v[56:59], v[20:23], v[76:79], v[56:59]
	s_setprio 0
	s_setprio 1
	v_mfma_f32_16x16x32_bf16 v[64:67], v[0:3], v[68:71], 0
	v_mfma_f32_16x16x32_bf16 v[68:71], v[8:11], v[68:71], 0
	v_mfma_f32_16x16x32_bf16 v[64:67], v[4:7], v[80:83], v[64:67]
	v_mfma_f32_16x16x32_bf16 v[68:71], v[12:15], v[80:83], v[68:71]
	v_mfma_f32_16x16x32_bf16 v[80:83], v[0:3], v[84:87], 0
	v_mfma_f32_16x16x32_bf16 v[84:87], v[8:11], v[84:87], 0
	v_mfma_f32_16x16x32_bf16 v[80:83], v[4:7], v[96:99], v[80:83]
	v_mfma_f32_16x16x32_bf16 v[84:87], v[12:15], v[96:99], v[84:87]
	v_mfma_f32_16x16x32_bf16 v[96:99], v[0:3], v[88:91], 0
	v_mfma_f32_16x16x32_bf16 v[88:91], v[8:11], v[88:91], 0
	v_mfma_f32_16x16x32_bf16 v[132:135], v[12:15], v[92:95], v[88:91]
	v_mfma_f32_16x16x32_bf16 v[88:91], v[0:3], v[72:75], 0
	v_mfma_f32_16x16x32_bf16 v[72:75], v[8:11], v[72:75], 0
	v_mfma_f32_16x16x32_bf16 v[128:131], v[4:7], v[92:95], v[96:99]
	v_mfma_f32_16x16x32_bf16 v[136:139], v[4:7], v[76:79], v[88:91]
	v_mfma_f32_16x16x32_bf16 v[140:143], v[12:15], v[76:79], v[72:75]
	s_setprio 0
	s_barrier
	ds_read_b128 v[104:107], v164 offset:16384
	ds_read_b128 v[108:111], v164 offset:17408
	ds_read_b128 v[96:99], v164 offset:18432
	ds_read_b128 v[100:103], v164 offset:19456
	ds_read_b128 v[88:91], v164 offset:20480
	ds_read_b128 v[92:95], v164 offset:21504
	ds_read_b128 v[72:75], v164 offset:22528
	ds_read_b128 v[76:79], v164 offset:23552
	s_mov_b32 m0, s55
	s_nop 0
	global_load_lds_dwordx4 v160, s[52:53]
	s_add_u32 s52, s80, 0x12000
	s_addc_u32 s53, s81, 0
	s_mov_b32 m0, s56
	s_nop 0
	global_load_lds_dwordx4 v160, s[52:53]
	s_add_u32 s52, s80, 0x14000
	s_addc_u32 s53, s81, 0
	s_mov_b32 m0, s57
	s_nop 0
	global_load_lds_dwordx4 v160, s[52:53]
	s_add_u32 s52, s80, 0x16000
	s_addc_u32 s53, s81, 0
	s_mov_b32 m0, s58
	s_nop 0
	global_load_lds_dwordx4 v160, s[52:53]
	s_nop 0
	s_mov_b32 m0, s54
	s_nop 0
	global_load_lds_dwordx4 v160, s[8:9]
	s_add_u32 s8, s48, 0x12000
	s_addc_u32 s9, s49, 0
	s_mov_b32 m0, s59
	s_nop 0
	global_load_lds_dwordx4 v160, s[8:9]
	s_and_b64 vcc, exec, s[2:3]
	s_cbranch_vccz .LBB0_496
	s_waitcnt vmcnt(24)
	s_cbranch_execnz .LBB0_424

.LBB0_425:
	ds_read_b128 v[128:131], v162
	ds_read_b128 v[132:135], v162 offset:1024
	ds_read_b128 v[136:139], v162 offset:2048
	ds_read_b128 v[140:143], v162 offset:3072
	ds_read_b128 v[152:155], v163
	ds_read_b128 v[156:159], v163 offset:1024
	ds_read_b128 v[168:171], v163 offset:2048
	ds_read_b128 v[172:175], v163 offset:3072
	s_add_u32 s48, s52, 0x10000
	s_addc_u32 s49, s53, 0
	s_cmp_eq_u32 s79, 60
	s_cselect_b32 s80, s10, s48
	s_cselect_b32 s81, s5, s49
	s_cselect_b32 s96, s47, s77
	s_cselect_b32 s97, s45, s78
	s_add_u32 s2, s80, 0x8000
	s_addc_u32 s3, s81, 0
	ds_read_b128 v[176:179], v164
	ds_read_b128 v[180:183], v164 offset:1024
	ds_read_b128 v[184:187], v164 offset:2048
	ds_read_b128 v[188:191], v164 offset:3072
	ds_read_b128 v[192:195], v164 offset:4096
	ds_read_b128 v[196:199], v164 offset:5120
	ds_read_b128 v[200:203], v164 offset:6144
	ds_read_b128 v[204:207], v164 offset:7168
	s_add_u32 s82, s52, 0xc000
	s_addc_u32 s83, s53, 0
	s_mov_b32 m0, s70
	s_nop 0
	global_load_lds_dwordx4 v160, s[82:83]
	s_add_u32 s52, s52, 0xe000
	s_addc_u32 s53, s53, 0
	s_mov_b32 m0, s71
	s_nop 0
	global_load_lds_dwordx4 v160, s[52:53]
	s_waitcnt vmcnt(8)
	s_waitcnt lgkmcnt(0)
	s_add_u32 s52, s96, 0x8000
	s_addc_u32 s53, s97, 0
	s_barrier
	s_setprio 1
	s_waitcnt lgkmcnt(7)
	s_waitcnt lgkmcnt(0)
	v_mfma_f32_16x16x32_bf16 v[124:127], v[128:131], v[176:179], v[124:127]
	v_mfma_f32_16x16x32_bf16 v[124:127], v[132:135], v[180:183], v[124:127]
	v_mfma_f32_16x16x32_bf16 v[120:123], v[136:139], v[176:179], v[120:123]
	v_mfma_f32_16x16x32_bf16 v[120:123], v[140:143], v[180:183], v[120:123]
	v_mfma_f32_16x16x32_bf16 v[104:107], v[136:139], v[184:187], v[104:107]
	v_mfma_f32_16x16x32_bf16 v[104:107], v[140:143], v[188:191], v[104:107]
	v_mfma_f32_16x16x32_bf16 v[108:111], v[128:131], v[184:187], v[108:111]
	v_mfma_f32_16x16x32_bf16 v[108:111], v[132:135], v[188:191], v[108:111]
	v_mfma_f32_16x16x32_bf16 v[92:95], v[128:131], v[192:195], v[92:95]
	v_mfma_f32_16x16x32_bf16 v[92:95], v[132:135], v[196:199], v[92:95]
	v_mfma_f32_16x16x32_bf16 v[88:91], v[136:139], v[192:195], v[88:91]
	v_mfma_f32_16x16x32_bf16 v[88:91], v[140:143], v[196:199], v[88:91]
	v_mfma_f32_16x16x32_bf16 v[72:75], v[136:139], v[200:203], v[72:75]
	v_mfma_f32_16x16x32_bf16 v[72:75], v[140:143], v[204:207], v[72:75]
	v_mfma_f32_16x16x32_bf16 v[76:79], v[128:131], v[200:203], v[76:79]
	v_mfma_f32_16x16x32_bf16 v[76:79], v[132:135], v[204:207], v[76:79]
	s_setprio 0
	s_setprio 1
	s_waitcnt lgkmcnt(0)
	v_mfma_f32_16x16x32_bf16 v[116:119], v[152:155], v[176:179], v[116:119]
	v_mfma_f32_16x16x32_bf16 v[116:119], v[156:159], v[180:183], v[116:119]
	v_mfma_f32_16x16x32_bf16 v[112:115], v[168:171], v[176:179], v[112:115]
	v_mfma_f32_16x16x32_bf16 v[112:115], v[172:175], v[180:183], v[112:115]
	v_mfma_f32_16x16x32_bf16 v[96:99], v[168:171], v[184:187], v[96:99]
	v_mfma_f32_16x16x32_bf16 v[96:99], v[172:175], v[188:191], v[96:99]
	v_mfma_f32_16x16x32_bf16 v[100:103], v[152:155], v[184:187], v[100:103]
	v_mfma_f32_16x16x32_bf16 v[100:103], v[156:159], v[188:191], v[100:103]
	v_mfma_f32_16x16x32_bf16 v[84:87], v[152:155], v[192:195], v[84:87]
	v_mfma_f32_16x16x32_bf16 v[84:87], v[156:159], v[196:199], v[84:87]
	v_mfma_f32_16x16x32_bf16 v[80:83], v[168:171], v[192:195], v[80:83]
	v_mfma_f32_16x16x32_bf16 v[80:83], v[172:175], v[196:199], v[80:83]
	v_mfma_f32_16x16x32_bf16 v[64:67], v[168:171], v[200:203], v[64:67]
	v_mfma_f32_16x16x32_bf16 v[64:67], v[172:175], v[204:207], v[64:67]
	v_mfma_f32_16x16x32_bf16 v[68:71], v[152:155], v[200:203], v[68:71]
	v_mfma_f32_16x16x32_bf16 v[68:71], v[156:159], v[204:207], v[68:71]
	s_setprio 0
	s_barrier
	s_add_u32 s82, s96, 0x2000
	ds_read_b128 v[176:179], v164 offset:16384
	ds_read_b128 v[180:183], v164 offset:17408
	ds_read_b128 v[184:187], v164 offset:18432
	ds_read_b128 v[188:191], v164 offset:19456
	ds_read_b128 v[192:195], v164 offset:20480
	ds_read_b128 v[196:199], v164 offset:21504
	ds_read_b128 v[200:203], v164 offset:22528
	ds_read_b128 v[204:207], v164 offset:23552
	s_mov_b32 m0, s55
	s_nop 0
	global_load_lds_dwordx4 v160, s[96:97]
	s_addc_u32 s83, s97, 0
	s_mov_b32 m0, s56
	s_nop 0
	global_load_lds_dwordx4 v160, s[82:83]
	s_add_u32 s82, s96, 0x4000
	s_addc_u32 s83, s97, 0
	s_mov_b32 m0, s57
	s_nop 0
	global_load_lds_dwordx4 v160, s[82:83]
	s_add_u32 s82, s96, 0x6000
	s_addc_u32 s83, s97, 0
	s_mov_b32 m0, s58
	s_nop 0
	global_load_lds_dwordx4 v160, s[82:83]
	s_add_u32 s82, s80, 0x2000
	s_mov_b32 m0, s54
	s_nop 0
	global_load_lds_dwordx4 v160, s[80:81]
	s_addc_u32 s83, s81, 0
	s_mov_b32 m0, s59
	s_nop 0
	global_load_lds_dwordx4 v160, s[82:83]
	s_waitcnt vmcnt(8)
	s_waitcnt lgkmcnt(0)
	s_barrier
	s_setprio 1
	s_waitcnt lgkmcnt(7)
	s_waitcnt lgkmcnt(0)
	v_mfma_f32_16x16x32_bf16 v[60:63], v[128:131], v[176:179], v[60:63]
	v_mfma_f32_16x16x32_bf16 v[60:63], v[132:135], v[180:183], v[60:63]
	v_mfma_f32_16x16x32_bf16 v[56:59], v[136:139], v[176:179], v[56:59]
	v_mfma_f32_16x16x32_bf16 v[56:59], v[140:143], v[180:183], v[56:59]
	v_mfma_f32_16x16x32_bf16 v[40:43], v[136:139], v[184:187], v[40:43]
	v_mfma_f32_16x16x32_bf16 v[40:43], v[140:143], v[188:191], v[40:43]
	v_mfma_f32_16x16x32_bf16 v[44:47], v[128:131], v[184:187], v[44:47]
	v_mfma_f32_16x16x32_bf16 v[44:47], v[132:135], v[188:191], v[44:47]
	v_mfma_f32_16x16x32_bf16 v[28:31], v[128:131], v[192:195], v[28:31]
	v_mfma_f32_16x16x32_bf16 v[28:31], v[132:135], v[196:199], v[28:31]
	v_mfma_f32_16x16x32_bf16 v[24:27], v[136:139], v[192:195], v[24:27]
	v_mfma_f32_16x16x32_bf16 v[24:27], v[140:143], v[196:199], v[24:27]
	v_mfma_f32_16x16x32_bf16 v[8:11], v[136:139], v[200:203], v[8:11]
	v_mfma_f32_16x16x32_bf16 v[8:11], v[140:143], v[204:207], v[8:11]
	v_mfma_f32_16x16x32_bf16 v[12:15], v[128:131], v[200:203], v[12:15]
	v_mfma_f32_16x16x32_bf16 v[12:15], v[132:135], v[204:207], v[12:15]
	s_setprio 0
	s_setprio 1
	s_waitcnt lgkmcnt(0)
	v_mfma_f32_16x16x32_bf16 v[52:55], v[152:155], v[176:179], v[52:55]
	v_mfma_f32_16x16x32_bf16 v[52:55], v[156:159], v[180:183], v[52:55]
	v_mfma_f32_16x16x32_bf16 v[48:51], v[168:171], v[176:179], v[48:51]
	v_mfma_f32_16x16x32_bf16 v[48:51], v[172:175], v[180:183], v[48:51]
	v_mfma_f32_16x16x32_bf16 v[32:35], v[168:171], v[184:187], v[32:35]
	v_mfma_f32_16x16x32_bf16 v[32:35], v[172:175], v[188:191], v[32:35]
	v_mfma_f32_16x16x32_bf16 v[36:39], v[152:155], v[184:187], v[36:39]
	v_mfma_f32_16x16x32_bf16 v[36:39], v[156:159], v[188:191], v[36:39]
	v_mfma_f32_16x16x32_bf16 v[20:23], v[152:155], v[192:195], v[20:23]
	v_mfma_f32_16x16x32_bf16 v[20:23], v[156:159], v[196:199], v[20:23]
	v_mfma_f32_16x16x32_bf16 v[16:19], v[168:171], v[192:195], v[16:19]
	v_mfma_f32_16x16x32_bf16 v[16:19], v[172:175], v[196:199], v[16:19]
	v_mfma_f32_16x16x32_bf16 v[0:3], v[168:171], v[200:203], v[0:3]
	v_mfma_f32_16x16x32_bf16 v[0:3], v[172:175], v[204:207], v[0:3]
	v_mfma_f32_16x16x32_bf16 v[4:7], v[152:155], v[200:203], v[4:7]
	v_mfma_f32_16x16x32_bf16 v[4:7], v[156:159], v[204:207], v[4:7]
	s_setprio 0
	s_barrier
	ds_read_b128 v[128:131], v148
	ds_read_b128 v[132:135], v148 offset:1024
	ds_read_b128 v[136:139], v148 offset:2048
	ds_read_b128 v[140:143], v148 offset:3072
	ds_read_b128 v[152:155], v150
	ds_read_b128 v[156:159], v150 offset:1024
	ds_read_b128 v[168:171], v150 offset:2048
	ds_read_b128 v[172:175], v150 offset:3072
	ds_read_b128 v[176:179], v164 offset:32768
	ds_read_b128 v[180:183], v164 offset:33792
	ds_read_b128 v[184:187], v164 offset:34816
	ds_read_b128 v[188:191], v164 offset:35840
	ds_read_b128 v[192:195], v164 offset:36864
	ds_read_b128 v[196:199], v164 offset:37888
	ds_read_b128 v[200:203], v164 offset:38912
	ds_read_b128 v[204:207], v164 offset:39936
	s_add_u32 s82, s80, 0x4000
	s_addc_u32 s83, s81, 0
	s_mov_b32 m0, s60
	s_nop 0
	global_load_lds_dwordx4 v160, s[82:83]
	s_add_u32 s82, s80, 0x6000
	s_addc_u32 s83, s81, 0
	s_mov_b32 m0, s61
	s_nop 0
	global_load_lds_dwordx4 v160, s[82:83]
	s_waitcnt vmcnt(8)
	s_waitcnt lgkmcnt(0)
	s_barrier
	s_setprio 1
	s_waitcnt lgkmcnt(7)
	s_waitcnt lgkmcnt(0)
	v_mfma_f32_16x16x32_bf16 v[124:127], v[128:131], v[176:179], v[124:127]
	v_mfma_f32_16x16x32_bf16 v[124:127], v[132:135], v[180:183], v[124:127]
	v_mfma_f32_16x16x32_bf16 v[120:123], v[136:139], v[176:179], v[120:123]
	v_mfma_f32_16x16x32_bf16 v[120:123], v[140:143], v[180:183], v[120:123]
	v_mfma_f32_16x16x32_bf16 v[104:107], v[136:139], v[184:187], v[104:107]
	v_mfma_f32_16x16x32_bf16 v[104:107], v[140:143], v[188:191], v[104:107]
	v_mfma_f32_16x16x32_bf16 v[108:111], v[128:131], v[184:187], v[108:111]
	v_mfma_f32_16x16x32_bf16 v[108:111], v[132:135], v[188:191], v[108:111]
	v_mfma_f32_16x16x32_bf16 v[92:95], v[128:131], v[192:195], v[92:95]
	v_mfma_f32_16x16x32_bf16 v[92:95], v[132:135], v[196:199], v[92:95]
	v_mfma_f32_16x16x32_bf16 v[88:91], v[136:139], v[192:195], v[88:91]
	v_mfma_f32_16x16x32_bf16 v[88:91], v[140:143], v[196:199], v[88:91]
	v_mfma_f32_16x16x32_bf16 v[72:75], v[136:139], v[200:203], v[72:75]
	v_mfma_f32_16x16x32_bf16 v[72:75], v[140:143], v[204:207], v[72:75]
	v_mfma_f32_16x16x32_bf16 v[76:79], v[128:131], v[200:203], v[76:79]
	v_mfma_f32_16x16x32_bf16 v[76:79], v[132:135], v[204:207], v[76:79]
	s_setprio 0
	s_setprio 1
	s_waitcnt lgkmcnt(0)
	v_mfma_f32_16x16x32_bf16 v[116:119], v[152:155], v[176:179], v[116:119]
	v_mfma_f32_16x16x32_bf16 v[116:119], v[156:159], v[180:183], v[116:119]
	v_mfma_f32_16x16x32_bf16 v[112:115], v[168:171], v[176:179], v[112:115]
	v_mfma_f32_16x16x32_bf16 v[112:115], v[172:175], v[180:183], v[112:115]
	v_mfma_f32_16x16x32_bf16 v[96:99], v[168:171], v[184:187], v[96:99]
	v_mfma_f32_16x16x32_bf16 v[96:99], v[172:175], v[188:191], v[96:99]
	v_mfma_f32_16x16x32_bf16 v[100:103], v[152:155], v[184:187], v[100:103]
	v_mfma_f32_16x16x32_bf16 v[100:103], v[156:159], v[188:191], v[100:103]
	v_mfma_f32_16x16x32_bf16 v[84:87], v[152:155], v[192:195], v[84:87]
	v_mfma_f32_16x16x32_bf16 v[84:87], v[156:159], v[196:199], v[84:87]
	v_mfma_f32_16x16x32_bf16 v[80:83], v[168:171], v[192:195], v[80:83]
	v_mfma_f32_16x16x32_bf16 v[80:83], v[172:175], v[196:199], v[80:83]
	v_mfma_f32_16x16x32_bf16 v[64:67], v[168:171], v[200:203], v[64:67]
	v_mfma_f32_16x16x32_bf16 v[64:67], v[172:175], v[204:207], v[64:67]
	v_mfma_f32_16x16x32_bf16 v[68:71], v[152:155], v[200:203], v[68:71]
	v_mfma_f32_16x16x32_bf16 v[68:71], v[156:159], v[204:207], v[68:71]
	s_setprio 0
	s_barrier
	ds_read_b128 v[176:179], v164 offset:49152
	ds_read_b128 v[180:183], v164 offset:50176
	ds_read_b128 v[184:187], v164 offset:51200
	ds_read_b128 v[188:191], v164 offset:52224
	ds_read_b128 v[192:195], v164 offset:53248
	ds_read_b128 v[196:199], v164 offset:54272
	ds_read_b128 v[200:203], v164 offset:55296
	ds_read_b128 v[204:207], v164 offset:56320
	s_mov_b32 m0, s64
	s_nop 0
	global_load_lds_dwordx4 v160, s[52:53]
	s_add_u32 s52, s96, 0xa000
	s_addc_u32 s53, s97, 0
	s_mov_b32 m0, s65
	s_nop 0
	global_load_lds_dwordx4 v160, s[52:53]
	s_add_u32 s52, s96, 0xc000
	s_addc_u32 s53, s97, 0
	s_mov_b32 m0, s68
	s_nop 0
	global_load_lds_dwordx4 v160, s[52:53]
	s_add_u32 s52, s96, 0xe000
	s_addc_u32 s53, s97, 0
	s_mov_b32 m0, s69
	s_nop 0
	global_load_lds_dwordx4 v160, s[52:53]
	s_nop 0
	s_mov_b32 m0, s66
	s_nop 0
	global_load_lds_dwordx4 v160, s[2:3]
	s_add_u32 s2, s80, 0xa000
	s_addc_u32 s3, s81, 0
	s_mov_b32 m0, s67
	s_nop 0
	global_load_lds_dwordx4 v160, s[2:3]
	s_waitcnt vmcnt(8)
	s_waitcnt lgkmcnt(0)
	s_barrier
	s_setprio 1
	s_waitcnt lgkmcnt(7)
	s_waitcnt lgkmcnt(0)
	v_mfma_f32_16x16x32_bf16 v[60:63], v[128:131], v[176:179], v[60:63]
	v_mfma_f32_16x16x32_bf16 v[60:63], v[132:135], v[180:183], v[60:63]
	v_mfma_f32_16x16x32_bf16 v[56:59], v[136:139], v[176:179], v[56:59]
	v_mfma_f32_16x16x32_bf16 v[56:59], v[140:143], v[180:183], v[56:59]
	v_mfma_f32_16x16x32_bf16 v[40:43], v[136:139], v[184:187], v[40:43]
	v_mfma_f32_16x16x32_bf16 v[40:43], v[140:143], v[188:191], v[40:43]
	v_mfma_f32_16x16x32_bf16 v[44:47], v[128:131], v[184:187], v[44:47]
	v_mfma_f32_16x16x32_bf16 v[44:47], v[132:135], v[188:191], v[44:47]
	v_mfma_f32_16x16x32_bf16 v[28:31], v[128:131], v[192:195], v[28:31]
	v_mfma_f32_16x16x32_bf16 v[28:31], v[132:135], v[196:199], v[28:31]
	v_mfma_f32_16x16x32_bf16 v[24:27], v[136:139], v[192:195], v[24:27]
	v_mfma_f32_16x16x32_bf16 v[24:27], v[140:143], v[196:199], v[24:27]
	v_mfma_f32_16x16x32_bf16 v[8:11], v[136:139], v[200:203], v[8:11]
	v_mfma_f32_16x16x32_bf16 v[8:11], v[140:143], v[204:207], v[8:11]
	v_mfma_f32_16x16x32_bf16 v[12:15], v[128:131], v[200:203], v[12:15]
	v_mfma_f32_16x16x32_bf16 v[12:15], v[132:135], v[204:207], v[12:15]
	s_setprio 0
	s_setprio 1
	s_waitcnt lgkmcnt(0)
	v_mfma_f32_16x16x32_bf16 v[52:55], v[152:155], v[176:179], v[52:55]
	v_mfma_f32_16x16x32_bf16 v[52:55], v[156:159], v[180:183], v[52:55]
	v_mfma_f32_16x16x32_bf16 v[48:51], v[168:171], v[176:179], v[48:51]
	v_mfma_f32_16x16x32_bf16 v[48:51], v[172:175], v[180:183], v[48:51]
	v_mfma_f32_16x16x32_bf16 v[32:35], v[168:171], v[184:187], v[32:35]
	v_mfma_f32_16x16x32_bf16 v[32:35], v[172:175], v[188:191], v[32:35]
	v_mfma_f32_16x16x32_bf16 v[36:39], v[152:155], v[184:187], v[36:39]
	v_mfma_f32_16x16x32_bf16 v[36:39], v[156:159], v[188:191], v[36:39]
	v_mfma_f32_16x16x32_bf16 v[20:23], v[152:155], v[192:195], v[20:23]
	v_mfma_f32_16x16x32_bf16 v[20:23], v[156:159], v[196:199], v[20:23]
	v_mfma_f32_16x16x32_bf16 v[16:19], v[168:171], v[192:195], v[16:19]
	v_mfma_f32_16x16x32_bf16 v[16:19], v[172:175], v[196:199], v[16:19]
	v_mfma_f32_16x16x32_bf16 v[0:3], v[168:171], v[200:203], v[0:3]
	v_mfma_f32_16x16x32_bf16 v[0:3], v[172:175], v[204:207], v[0:3]
	v_mfma_f32_16x16x32_bf16 v[4:7], v[152:155], v[200:203], v[4:7]
	v_mfma_f32_16x16x32_bf16 v[4:7], v[156:159], v[204:207], v[4:7]
	s_setprio 0
	s_barrier
	s_add_i32 s79, s79, 2
	s_add_u32 s77, s77, 0x10000
	s_addc_u32 s78, s78, 0
	s_cmp_gt_u32 s79, 61
	s_mov_b64 s[52:53], s[48:49]
	s_cbranch_scc0 .LBB0_425
	s_and_b64 vcc, exec, s[14:15]
	s_cbranch_vccz .LBB0_428
	s_barrier

.LBB0_1402:
	s_add_u32 s44, s2, 0x10000
	s_waitcnt lgkmcnt(0)
	s_addc_u32 s45, s3, 0
	s_add_u32 s52, s56, 0x10000
	s_addc_u32 s53, s57, 0
	s_barrier
	s_setprio 1
	s_waitcnt lgkmcnt(7)
	s_waitcnt lgkmcnt(0)
	v_mfma_f32_16x16x32_bf16 v[32:35], v[16:19], v[68:71], 0
	v_mfma_f32_16x16x32_bf16 v[32:35], v[20:23], v[72:75], v[32:35]
	v_mfma_f32_16x16x32_bf16 v[36:39], v[24:27], v[68:71], 0
	v_mfma_f32_16x16x32_bf16 v[36:39], v[28:31], v[72:75], v[36:39]
	v_mfma_f32_16x16x32_bf16 v[44:47], v[24:27], v[84:87], 0
	v_mfma_f32_16x16x32_bf16 v[44:47], v[28:31], v[88:91], v[44:47]
	v_mfma_f32_16x16x32_bf16 v[40:43], v[16:19], v[84:87], 0
	v_mfma_f32_16x16x32_bf16 v[40:43], v[20:23], v[88:91], v[40:43]
	v_mfma_f32_16x16x32_bf16 v[48:51], v[16:19], v[92:95], 0
	v_mfma_f32_16x16x32_bf16 v[48:51], v[20:23], v[96:99], v[48:51]
	v_mfma_f32_16x16x32_bf16 v[52:55], v[24:27], v[92:95], 0
	v_mfma_f32_16x16x32_bf16 v[52:55], v[28:31], v[96:99], v[52:55]
	v_mfma_f32_16x16x32_bf16 v[60:63], v[24:27], v[76:79], 0
	v_mfma_f32_16x16x32_bf16 v[60:63], v[28:31], v[80:83], v[60:63]
	v_mfma_f32_16x16x32_bf16 v[56:59], v[16:19], v[76:79], 0
	v_mfma_f32_16x16x32_bf16 v[56:59], v[20:23], v[80:83], v[56:59]
	s_setprio 0
	s_setprio 1
	v_mfma_f32_16x16x32_bf16 v[64:67], v[0:3], v[68:71], 0
	v_mfma_f32_16x16x32_bf16 v[68:71], v[8:11], v[68:71], 0
	v_mfma_f32_16x16x32_bf16 v[64:67], v[4:7], v[72:75], v[64:67]
	v_mfma_f32_16x16x32_bf16 v[68:71], v[12:15], v[72:75], v[68:71]
	v_mfma_f32_16x16x32_bf16 v[72:75], v[0:3], v[84:87], 0
	v_mfma_f32_16x16x32_bf16 v[84:87], v[8:11], v[84:87], 0
	v_mfma_f32_16x16x32_bf16 v[72:75], v[4:7], v[88:91], v[72:75]
	v_mfma_f32_16x16x32_bf16 v[84:87], v[12:15], v[88:91], v[84:87]
	v_mfma_f32_16x16x32_bf16 v[88:91], v[0:3], v[92:95], 0
	v_mfma_f32_16x16x32_bf16 v[92:95], v[8:11], v[92:95], 0
	v_mfma_f32_16x16x32_bf16 v[88:91], v[4:7], v[96:99], v[88:91]
	v_mfma_f32_16x16x32_bf16 v[96:99], v[12:15], v[96:99], v[92:95]
	v_mfma_f32_16x16x32_bf16 v[92:95], v[0:3], v[76:79], 0
	v_mfma_f32_16x16x32_bf16 v[76:79], v[8:11], v[76:79], 0
	v_mfma_f32_16x16x32_bf16 v[108:111], v[4:7], v[80:83], v[92:95]
	v_mfma_f32_16x16x32_bf16 v[112:115], v[12:15], v[80:83], v[76:79]
	s_setprio 0
	s_barrier
	ds_read_b128 v[120:123], v214 offset:16384
	ds_read_b128 v[124:127], v214 offset:17408
	ds_read_b128 v[104:107], v214 offset:18432
	ds_read_b128 v[116:119], v214 offset:19456
	ds_read_b128 v[92:95], v214 offset:20480
	ds_read_b128 v[100:103], v214 offset:21504
	ds_read_b128 v[76:79], v214 offset:22528
	ds_read_b128 v[80:83], v214 offset:23552
	s_mov_b32 m0, s47
	s_nop 0
	global_load_lds_dwordx4 v210, s[52:53]
	s_add_u32 s52, s56, 0x12000
	s_addc_u32 s53, s57, 0
	s_mov_b32 m0, s49
	s_nop 0
	global_load_lds_dwordx4 v210, s[52:53]
	s_add_u32 s52, s56, 0x14000
	s_addc_u32 s53, s57, 0
	s_mov_b32 m0, s61
	s_nop 0
	global_load_lds_dwordx4 v210, s[52:53]
	s_add_u32 s52, s56, 0x16000
	s_addc_u32 s53, s57, 0
	s_mov_b32 m0, s62
	s_nop 0
	global_load_lds_dwordx4 v210, s[52:53]
	s_nop 0
	s_mov_b32 m0, s60
	s_nop 0
	global_load_lds_dwordx4 v210, s[44:45]
	s_add_u32 s44, s2, 0x12000
	s_addc_u32 s45, s3, 0
	s_mov_b32 m0, s63
	s_nop 0
	global_load_lds_dwordx4 v210, s[44:45]
	s_and_b64 vcc, exec, s[42:43]
	s_cbranch_vccz .LBB0_1429
	s_waitcnt vmcnt(24)
	s_cbranch_execnz .LBB0_1405

.LBB0_1406:
	ds_read_b128 v[72:75], v212
	ds_read_b128 v[84:87], v212 offset:1024
	ds_read_b128 v[96:99], v212 offset:2048
	ds_read_b128 v[108:111], v212 offset:3072
	ds_read_b128 v[112:115], v213
	ds_read_b128 v[136:139], v213 offset:1024
	ds_read_b128 v[148:151], v213 offset:2048
	ds_read_b128 v[160:163], v213 offset:3072
	s_cmp_eq_u32 s90, 60
	s_cselect_b32 s2, s82, s54
	s_cselect_b32 s3, s41, s55
	s_cselect_b32 s58, s83, s88
	s_cselect_b32 s59, s39, s89
	s_add_u32 s56, s2, 0x8000
	s_addc_u32 s57, s3, 0
	ds_read_b128 v[164:167], v214
	ds_read_b128 v[168:171], v214 offset:1024
	ds_read_b128 v[172:175], v214 offset:2048
	ds_read_b128 v[176:179], v214 offset:3072
	ds_read_b128 v[180:183], v214 offset:4096
	ds_read_b128 v[184:187], v214 offset:5120
	ds_read_b128 v[188:191], v214 offset:6144
	ds_read_b128 v[192:195], v214 offset:7168
	s_add_u32 s52, s54, 0xffffc000
	s_addc_u32 s53, s55, -1
	s_mov_b32 m0, s75
	s_nop 0
	global_load_lds_dwordx4 v210, s[52:53]
	s_add_u32 s52, s54, 0xffffe000
	s_addc_u32 s53, s55, -1
	s_mov_b32 m0, s78
	s_nop 0
	global_load_lds_dwordx4 v210, s[52:53]
	s_waitcnt vmcnt(8)
	s_waitcnt lgkmcnt(0)
	s_add_u32 s52, s58, 0x8000
	s_addc_u32 s53, s59, 0
	s_barrier
	s_setprio 1
	s_waitcnt lgkmcnt(7)
	v_mfma_f32_16x16x32_bf16 v[156:159], v[72:75], v[164:167], v[156:159]
	v_mfma_f32_16x16x32_bf16 v[152:155], v[96:99], v[164:167], v[152:155]
	s_waitcnt lgkmcnt(5)
	v_mfma_f32_16x16x32_bf16 v[132:135], v[72:75], v[172:175], v[132:135]
	v_mfma_f32_16x16x32_bf16 v[126:129], v[96:99], v[172:175], v[128:131]
	s_waitcnt lgkmcnt(3)
	v_mfma_f32_16x16x32_bf16 v[104:107], v[72:75], v[180:183], v[104:107]
	v_mfma_f32_16x16x32_bf16 v[100:103], v[96:99], v[180:183], v[100:103]
	s_waitcnt lgkmcnt(1)
	v_mfma_f32_16x16x32_bf16 v[80:83], v[72:75], v[188:191], v[80:83]
	v_mfma_f32_16x16x32_bf16 v[76:79], v[96:99], v[188:191], v[76:79]
	v_mfma_f32_16x16x32_bf16 v[156:159], v[84:87], v[168:171], v[156:159]
	v_mfma_f32_16x16x32_bf16 v[152:155], v[108:111], v[168:171], v[152:155]
	v_mfma_f32_16x16x32_bf16 v[132:135], v[84:87], v[176:179], v[132:135]
	v_mfma_f32_16x16x32_bf16 v[126:129], v[108:111], v[176:179], v[126:129]
	v_mfma_f32_16x16x32_bf16 v[104:107], v[84:87], v[184:187], v[104:107]
	v_mfma_f32_16x16x32_bf16 v[100:103], v[108:111], v[184:187], v[100:103]
	s_waitcnt lgkmcnt(0)
	v_mfma_f32_16x16x32_bf16 v[80:83], v[84:87], v[192:195], v[80:83]
	v_mfma_f32_16x16x32_bf16 v[76:79], v[108:111], v[192:195], v[76:79]
	s_setprio 0
	s_setprio 1
	s_waitcnt lgkmcnt(0)
	v_mfma_f32_16x16x32_bf16 v[144:147], v[112:115], v[164:167], v[144:147]
	v_mfma_f32_16x16x32_bf16 v[144:147], v[136:139], v[168:171], v[144:147]
	v_mfma_f32_16x16x32_bf16 v[140:143], v[148:151], v[164:167], v[140:143]
	v_mfma_f32_16x16x32_bf16 v[140:143], v[160:163], v[168:171], v[140:143]
	v_mfma_f32_16x16x32_bf16 v[116:119], v[148:151], v[172:175], v[116:119]
	v_mfma_f32_16x16x32_bf16 v[116:119], v[160:163], v[176:179], v[116:119]
	v_mfma_f32_16x16x32_bf16 v[120:123], v[112:115], v[172:175], v[120:123]
	v_mfma_f32_16x16x32_bf16 v[120:123], v[136:139], v[176:179], v[120:123]
	v_mfma_f32_16x16x32_bf16 v[92:95], v[112:115], v[180:183], v[92:95]
	v_mfma_f32_16x16x32_bf16 v[92:95], v[136:139], v[184:187], v[92:95]
	v_mfma_f32_16x16x32_bf16 v[88:91], v[148:151], v[180:183], v[88:91]
	v_mfma_f32_16x16x32_bf16 v[88:91], v[160:163], v[184:187], v[88:91]
	v_mfma_f32_16x16x32_bf16 v[64:67], v[148:151], v[188:191], v[64:67]
	v_mfma_f32_16x16x32_bf16 v[64:67], v[160:163], v[192:195], v[64:67]
	v_mfma_f32_16x16x32_bf16 v[68:71], v[112:115], v[188:191], v[68:71]
	v_mfma_f32_16x16x32_bf16 v[68:71], v[136:139], v[192:195], v[68:71]
	s_setprio 0
	s_barrier
	s_add_u32 s92, s58, 0x2000
	ds_read_b128 v[164:167], v214 offset:16384
	ds_read_b128 v[168:171], v214 offset:17408
	ds_read_b128 v[172:175], v214 offset:18432
	ds_read_b128 v[176:179], v214 offset:19456
	ds_read_b128 v[180:183], v214 offset:20480
	ds_read_b128 v[184:187], v214 offset:21504
	ds_read_b128 v[188:191], v214 offset:22528
	ds_read_b128 v[192:195], v214 offset:23552
	s_mov_b32 m0, s47
	s_nop 0
	global_load_lds_dwordx4 v210, s[58:59]
	s_addc_u32 s93, s59, 0
	s_mov_b32 m0, s49
	s_nop 0
	global_load_lds_dwordx4 v210, s[92:93]
	s_add_u32 s92, s58, 0x4000
	s_addc_u32 s93, s59, 0
	s_mov_b32 m0, s61
	s_nop 0
	global_load_lds_dwordx4 v210, s[92:93]
	s_add_u32 s92, s58, 0x6000
	s_addc_u32 s93, s59, 0
	s_mov_b32 m0, s62
	s_nop 0
	global_load_lds_dwordx4 v210, s[92:93]
	s_add_u32 s92, s2, 0x2000
	s_mov_b32 m0, s60
	s_nop 0
	global_load_lds_dwordx4 v210, s[2:3]
	s_addc_u32 s93, s3, 0
	s_mov_b32 m0, s63
	s_nop 0
	global_load_lds_dwordx4 v210, s[92:93]
	s_waitcnt vmcnt(8)
	s_waitcnt lgkmcnt(0)
	s_barrier
	s_setprio 1
	s_waitcnt lgkmcnt(7)
	s_waitcnt lgkmcnt(0)
	v_mfma_f32_16x16x32_bf16 v[60:63], v[72:75], v[164:167], v[60:63]
	v_mfma_f32_16x16x32_bf16 v[60:63], v[84:87], v[168:171], v[60:63]
	v_mfma_f32_16x16x32_bf16 v[56:59], v[96:99], v[164:167], v[56:59]
	v_mfma_f32_16x16x32_bf16 v[56:59], v[108:111], v[168:171], v[56:59]
	v_mfma_f32_16x16x32_bf16 v[40:43], v[96:99], v[172:175], v[40:43]
	v_mfma_f32_16x16x32_bf16 v[40:43], v[108:111], v[176:179], v[40:43]
	v_mfma_f32_16x16x32_bf16 v[44:47], v[72:75], v[172:175], v[44:47]
	v_mfma_f32_16x16x32_bf16 v[44:47], v[84:87], v[176:179], v[44:47]
	v_mfma_f32_16x16x32_bf16 v[28:31], v[72:75], v[180:183], v[28:31]
	v_mfma_f32_16x16x32_bf16 v[28:31], v[84:87], v[184:187], v[28:31]
	v_mfma_f32_16x16x32_bf16 v[24:27], v[96:99], v[180:183], v[24:27]
	v_mfma_f32_16x16x32_bf16 v[24:27], v[108:111], v[184:187], v[24:27]
	v_mfma_f32_16x16x32_bf16 v[8:11], v[96:99], v[188:191], v[8:11]
	v_mfma_f32_16x16x32_bf16 v[8:11], v[108:111], v[192:195], v[8:11]
	v_mfma_f32_16x16x32_bf16 v[12:15], v[72:75], v[188:191], v[12:15]
	v_mfma_f32_16x16x32_bf16 v[12:15], v[84:87], v[192:195], v[12:15]
	s_setprio 0
	s_setprio 1
	s_waitcnt lgkmcnt(0)
	v_mfma_f32_16x16x32_bf16 v[52:55], v[112:115], v[164:167], v[52:55]
	v_mfma_f32_16x16x32_bf16 v[52:55], v[136:139], v[168:171], v[52:55]
	v_mfma_f32_16x16x32_bf16 v[48:51], v[148:151], v[164:167], v[48:51]
	v_mfma_f32_16x16x32_bf16 v[48:51], v[160:163], v[168:171], v[48:51]
	v_mfma_f32_16x16x32_bf16 v[32:35], v[148:151], v[172:175], v[32:35]
	v_mfma_f32_16x16x32_bf16 v[32:35], v[160:163], v[176:179], v[32:35]
	v_mfma_f32_16x16x32_bf16 v[36:39], v[112:115], v[172:175], v[36:39]
	v_mfma_f32_16x16x32_bf16 v[36:39], v[136:139], v[176:179], v[36:39]
	v_mfma_f32_16x16x32_bf16 v[20:23], v[112:115], v[180:183], v[20:23]
	v_mfma_f32_16x16x32_bf16 v[20:23], v[136:139], v[184:187], v[20:23]
	v_mfma_f32_16x16x32_bf16 v[16:19], v[148:151], v[180:183], v[16:19]
	v_mfma_f32_16x16x32_bf16 v[16:19], v[160:163], v[184:187], v[16:19]
	v_mfma_f32_16x16x32_bf16 v[0:3], v[148:151], v[188:191], v[0:3]
	v_mfma_f32_16x16x32_bf16 v[0:3], v[160:163], v[192:195], v[0:3]
	v_mfma_f32_16x16x32_bf16 v[4:7], v[112:115], v[188:191], v[4:7]
	v_mfma_f32_16x16x32_bf16 v[4:7], v[136:139], v[192:195], v[4:7]
	s_setprio 0
	s_barrier
	ds_read_b128 v[72:75], v124
	ds_read_b128 v[84:87], v124 offset:1024
	ds_read_b128 v[96:99], v124 offset:2048
	ds_read_b128 v[108:111], v124 offset:3072
	ds_read_b128 v[112:115], v125
	ds_read_b128 v[136:139], v125 offset:1024
	ds_read_b128 v[148:151], v125 offset:2048
	ds_read_b128 v[160:163], v125 offset:3072
	ds_read_b128 v[164:167], v214 offset:32768
	ds_read_b128 v[168:171], v214 offset:33792
	ds_read_b128 v[172:175], v214 offset:34816
	ds_read_b128 v[176:179], v214 offset:35840
	ds_read_b128 v[180:183], v214 offset:36864
	ds_read_b128 v[184:187], v214 offset:37888
	ds_read_b128 v[188:191], v214 offset:38912
	ds_read_b128 v[192:195], v214 offset:39936
	s_add_u32 s92, s2, 0x4000
	s_addc_u32 s93, s3, 0
	s_mov_b32 m0, s64
	s_nop 0
	global_load_lds_dwordx4 v210, s[92:93]
	s_add_u32 s92, s2, 0x6000
	s_addc_u32 s93, s3, 0
	s_mov_b32 m0, s65
	s_nop 0
	global_load_lds_dwordx4 v210, s[92:93]
	s_waitcnt vmcnt(8)
	s_waitcnt lgkmcnt(0)
	s_barrier
	s_setprio 1
	s_waitcnt lgkmcnt(7)
	v_mfma_f32_16x16x32_bf16 v[156:159], v[72:75], v[164:167], v[156:159]
	v_mfma_f32_16x16x32_bf16 v[152:155], v[96:99], v[164:167], v[152:155]
	s_waitcnt lgkmcnt(5)
	v_mfma_f32_16x16x32_bf16 v[130:133], v[72:75], v[172:175], v[132:135]
	v_mfma_f32_16x16x32_bf16 v[126:129], v[96:99], v[172:175], v[126:129]
	s_waitcnt lgkmcnt(3)
	v_mfma_f32_16x16x32_bf16 v[104:107], v[72:75], v[180:183], v[104:107]
	v_mfma_f32_16x16x32_bf16 v[100:103], v[96:99], v[180:183], v[100:103]
	s_waitcnt lgkmcnt(1)
	v_mfma_f32_16x16x32_bf16 v[80:83], v[72:75], v[188:191], v[80:83]
	v_mfma_f32_16x16x32_bf16 v[76:79], v[96:99], v[188:191], v[76:79]
	v_mfma_f32_16x16x32_bf16 v[156:159], v[84:87], v[168:171], v[156:159]
	v_mfma_f32_16x16x32_bf16 v[152:155], v[108:111], v[168:171], v[152:155]
	v_mfma_f32_16x16x32_bf16 v[132:135], v[84:87], v[176:179], v[130:133]
	v_mfma_f32_16x16x32_bf16 v[128:131], v[108:111], v[176:179], v[126:129]
	v_mfma_f32_16x16x32_bf16 v[104:107], v[84:87], v[184:187], v[104:107]
	v_mfma_f32_16x16x32_bf16 v[100:103], v[108:111], v[184:187], v[100:103]
	s_waitcnt lgkmcnt(0)
	v_mfma_f32_16x16x32_bf16 v[80:83], v[84:87], v[192:195], v[80:83]
	v_mfma_f32_16x16x32_bf16 v[76:79], v[108:111], v[192:195], v[76:79]
	s_setprio 0
	s_setprio 1
	s_waitcnt lgkmcnt(0)
	v_mfma_f32_16x16x32_bf16 v[144:147], v[112:115], v[164:167], v[144:147]
	v_mfma_f32_16x16x32_bf16 v[144:147], v[136:139], v[168:171], v[144:147]
	v_mfma_f32_16x16x32_bf16 v[140:143], v[148:151], v[164:167], v[140:143]
	v_mfma_f32_16x16x32_bf16 v[140:143], v[160:163], v[168:171], v[140:143]
	v_mfma_f32_16x16x32_bf16 v[116:119], v[148:151], v[172:175], v[116:119]
	v_mfma_f32_16x16x32_bf16 v[116:119], v[160:163], v[176:179], v[116:119]
	v_mfma_f32_16x16x32_bf16 v[120:123], v[112:115], v[172:175], v[120:123]
	v_mfma_f32_16x16x32_bf16 v[120:123], v[136:139], v[176:179], v[120:123]
	v_mfma_f32_16x16x32_bf16 v[92:95], v[112:115], v[180:183], v[92:95]
	v_mfma_f32_16x16x32_bf16 v[92:95], v[136:139], v[184:187], v[92:95]
	v_mfma_f32_16x16x32_bf16 v[88:91], v[148:151], v[180:183], v[88:91]
	v_mfma_f32_16x16x32_bf16 v[88:91], v[160:163], v[184:187], v[88:91]
	v_mfma_f32_16x16x32_bf16 v[64:67], v[148:151], v[188:191], v[64:67]
	v_mfma_f32_16x16x32_bf16 v[64:67], v[160:163], v[192:195], v[64:67]
	v_mfma_f32_16x16x32_bf16 v[68:71], v[112:115], v[188:191], v[68:71]
	v_mfma_f32_16x16x32_bf16 v[68:71], v[136:139], v[192:195], v[68:71]
	s_setprio 0
	s_barrier
	ds_read_b128 v[164:167], v214 offset:49152
	ds_read_b128 v[168:171], v214 offset:50176
	ds_read_b128 v[172:175], v214 offset:51200
	ds_read_b128 v[176:179], v214 offset:52224
	ds_read_b128 v[180:183], v214 offset:53248
	ds_read_b128 v[184:187], v214 offset:54272
	ds_read_b128 v[188:191], v214 offset:55296
	ds_read_b128 v[192:195], v214 offset:56320
	s_mov_b32 m0, s69
	s_nop 0
	global_load_lds_dwordx4 v210, s[52:53]
	s_add_u32 s52, s58, 0xa000
	s_addc_u32 s53, s59, 0
	s_mov_b32 m0, s70
	s_nop 0
	global_load_lds_dwordx4 v210, s[52:53]
	s_add_u32 s52, s58, 0xc000
	s_addc_u32 s53, s59, 0
	s_mov_b32 m0, s73
	s_nop 0
	global_load_lds_dwordx4 v210, s[52:53]
	s_add_u32 s52, s58, 0xe000
	s_addc_u32 s53, s59, 0
	s_mov_b32 m0, s74
	s_nop 0
	global_load_lds_dwordx4 v210, s[52:53]
	s_add_u32 s2, s2, 0xa000
	s_mov_b32 m0, s71
	s_nop 0
	global_load_lds_dwordx4 v210, s[56:57]
	s_addc_u32 s3, s3, 0
	s_mov_b32 m0, s72
	s_nop 0
	global_load_lds_dwordx4 v210, s[2:3]
	s_waitcnt vmcnt(8)
	s_waitcnt lgkmcnt(0)
	s_barrier
	s_setprio 1
	s_waitcnt lgkmcnt(7)
	s_waitcnt lgkmcnt(0)
	v_mfma_f32_16x16x32_bf16 v[60:63], v[72:75], v[164:167], v[60:63]
	v_mfma_f32_16x16x32_bf16 v[60:63], v[84:87], v[168:171], v[60:63]
	v_mfma_f32_16x16x32_bf16 v[56:59], v[96:99], v[164:167], v[56:59]
	v_mfma_f32_16x16x32_bf16 v[56:59], v[108:111], v[168:171], v[56:59]
	v_mfma_f32_16x16x32_bf16 v[40:43], v[96:99], v[172:175], v[40:43]
	v_mfma_f32_16x16x32_bf16 v[40:43], v[108:111], v[176:179], v[40:43]
	v_mfma_f32_16x16x32_bf16 v[44:47], v[72:75], v[172:175], v[44:47]
	v_mfma_f32_16x16x32_bf16 v[44:47], v[84:87], v[176:179], v[44:47]
	v_mfma_f32_16x16x32_bf16 v[28:31], v[72:75], v[180:183], v[28:31]
	v_mfma_f32_16x16x32_bf16 v[28:31], v[84:87], v[184:187], v[28:31]
	v_mfma_f32_16x16x32_bf16 v[24:27], v[96:99], v[180:183], v[24:27]
	v_mfma_f32_16x16x32_bf16 v[24:27], v[108:111], v[184:187], v[24:27]
	v_mfma_f32_16x16x32_bf16 v[8:11], v[96:99], v[188:191], v[8:11]
	v_mfma_f32_16x16x32_bf16 v[8:11], v[108:111], v[192:195], v[8:11]
	v_mfma_f32_16x16x32_bf16 v[12:15], v[72:75], v[188:191], v[12:15]
	v_mfma_f32_16x16x32_bf16 v[12:15], v[84:87], v[192:195], v[12:15]
	s_setprio 0
	s_setprio 1
	s_waitcnt lgkmcnt(0)
	v_mfma_f32_16x16x32_bf16 v[52:55], v[112:115], v[164:167], v[52:55]
	v_mfma_f32_16x16x32_bf16 v[52:55], v[136:139], v[168:171], v[52:55]
	v_mfma_f32_16x16x32_bf16 v[48:51], v[148:151], v[164:167], v[48:51]
	v_mfma_f32_16x16x32_bf16 v[48:51], v[160:163], v[168:171], v[48:51]
	v_mfma_f32_16x16x32_bf16 v[32:35], v[148:151], v[172:175], v[32:35]
	v_mfma_f32_16x16x32_bf16 v[32:35], v[160:163], v[176:179], v[32:35]
	v_mfma_f32_16x16x32_bf16 v[36:39], v[112:115], v[172:175], v[36:39]
	v_mfma_f32_16x16x32_bf16 v[36:39], v[136:139], v[176:179], v[36:39]
	v_mfma_f32_16x16x32_bf16 v[20:23], v[112:115], v[180:183], v[20:23]
	v_mfma_f32_16x16x32_bf16 v[20:23], v[136:139], v[184:187], v[20:23]
	v_mfma_f32_16x16x32_bf16 v[16:19], v[148:151], v[180:183], v[16:19]
	v_mfma_f32_16x16x32_bf16 v[16:19], v[160:163], v[184:187], v[16:19]
	v_mfma_f32_16x16x32_bf16 v[0:3], v[148:151], v[188:191], v[0:3]
	v_mfma_f32_16x16x32_bf16 v[0:3], v[160:163], v[192:195], v[0:3]
	v_mfma_f32_16x16x32_bf16 v[4:7], v[112:115], v[188:191], v[4:7]
	v_mfma_f32_16x16x32_bf16 v[4:7], v[136:139], v[192:195], v[4:7]
	s_setprio 0
	s_barrier
	s_add_i32 s90, s90, 2
	s_add_u32 s54, s54, 0x10000
	s_addc_u32 s55, s55, 0
	s_add_u32 s88, s88, 0x10000
	s_addc_u32 s89, s89, 0
	s_cmp_gt_u32 s90, 61
	s_cbranch_scc0 .LBB0_1406
	s_and_b64 vcc, exec, s[12:13]
	s_cbranch_vccz .LBB0_1409
	s_barrier

.LBB0_1501:
	s_add_u32 s48, s2, 0x10000
	s_waitcnt lgkmcnt(0)
	s_addc_u32 s49, s3, 0
	s_add_u32 s52, s58, 0x10000
	s_addc_u32 s53, s59, 0
	s_barrier
	s_setprio 1
	s_waitcnt lgkmcnt(7)
	s_waitcnt lgkmcnt(0)
	v_mfma_f32_16x16x32_bf16 v[32:35], v[16:19], v[68:71], 0
	v_mfma_f32_16x16x32_bf16 v[32:35], v[20:23], v[80:83], v[32:35]
	v_mfma_f32_16x16x32_bf16 v[36:39], v[24:27], v[68:71], 0
	v_mfma_f32_16x16x32_bf16 v[36:39], v[28:31], v[80:83], v[36:39]
	v_mfma_f32_16x16x32_bf16 v[44:47], v[24:27], v[84:87], 0
	v_mfma_f32_16x16x32_bf16 v[44:47], v[28:31], v[96:99], v[44:47]
	v_mfma_f32_16x16x32_bf16 v[40:43], v[16:19], v[84:87], 0
	v_mfma_f32_16x16x32_bf16 v[40:43], v[20:23], v[96:99], v[40:43]
	v_mfma_f32_16x16x32_bf16 v[48:51], v[16:19], v[88:91], 0
	v_mfma_f32_16x16x32_bf16 v[48:51], v[20:23], v[92:95], v[48:51]
	v_mfma_f32_16x16x32_bf16 v[52:55], v[24:27], v[88:91], 0
	v_mfma_f32_16x16x32_bf16 v[52:55], v[28:31], v[92:95], v[52:55]
	v_mfma_f32_16x16x32_bf16 v[60:63], v[24:27], v[72:75], 0
	v_mfma_f32_16x16x32_bf16 v[60:63], v[28:31], v[76:79], v[60:63]
	v_mfma_f32_16x16x32_bf16 v[56:59], v[16:19], v[72:75], 0
	v_mfma_f32_16x16x32_bf16 v[56:59], v[20:23], v[76:79], v[56:59]
	s_setprio 0
	s_setprio 1
	v_mfma_f32_16x16x32_bf16 v[64:67], v[0:3], v[68:71], 0
	v_mfma_f32_16x16x32_bf16 v[68:71], v[8:11], v[68:71], 0
	v_mfma_f32_16x16x32_bf16 v[64:67], v[4:7], v[80:83], v[64:67]
	v_mfma_f32_16x16x32_bf16 v[68:71], v[12:15], v[80:83], v[68:71]
	v_mfma_f32_16x16x32_bf16 v[80:83], v[0:3], v[84:87], 0
	v_mfma_f32_16x16x32_bf16 v[84:87], v[8:11], v[84:87], 0
	v_mfma_f32_16x16x32_bf16 v[80:83], v[4:7], v[96:99], v[80:83]
	v_mfma_f32_16x16x32_bf16 v[84:87], v[12:15], v[96:99], v[84:87]
	v_mfma_f32_16x16x32_bf16 v[96:99], v[0:3], v[88:91], 0
	v_mfma_f32_16x16x32_bf16 v[88:91], v[8:11], v[88:91], 0
	v_mfma_f32_16x16x32_bf16 v[132:135], v[12:15], v[92:95], v[88:91]
	v_mfma_f32_16x16x32_bf16 v[88:91], v[0:3], v[72:75], 0
	v_mfma_f32_16x16x32_bf16 v[72:75], v[8:11], v[72:75], 0
	v_mfma_f32_16x16x32_bf16 v[128:131], v[4:7], v[92:95], v[96:99]
	v_mfma_f32_16x16x32_bf16 v[136:139], v[4:7], v[76:79], v[88:91]
	v_mfma_f32_16x16x32_bf16 v[140:143], v[12:15], v[76:79], v[72:75]
	s_setprio 0
	s_barrier
	ds_read_b128 v[104:107], v158 offset:16384
	ds_read_b128 v[108:111], v158 offset:17408
	ds_read_b128 v[96:99], v158 offset:18432
	ds_read_b128 v[100:103], v158 offset:19456
	ds_read_b128 v[88:91], v158 offset:20480
	ds_read_b128 v[92:95], v158 offset:21504
	ds_read_b128 v[72:75], v158 offset:22528
	ds_read_b128 v[76:79], v158 offset:23552
	s_mov_b32 m0, s57
	s_nop 0
	global_load_lds_dwordx4 v154, s[52:53]
	s_add_u32 s52, s58, 0x12000
	s_addc_u32 s53, s59, 0
	s_mov_b32 m0, s67
	s_nop 0
	global_load_lds_dwordx4 v154, s[52:53]
	s_add_u32 s52, s58, 0x14000
	s_addc_u32 s53, s59, 0
	s_mov_b32 m0, s68
	s_nop 0
	global_load_lds_dwordx4 v154, s[52:53]
	s_add_u32 s52, s58, 0x16000
	s_addc_u32 s53, s59, 0
	s_mov_b32 m0, s69
	s_nop 0
	global_load_lds_dwordx4 v154, s[52:53]
	s_nop 0
	s_mov_b32 m0, s66
	s_nop 0
	global_load_lds_dwordx4 v154, s[48:49]
	s_add_u32 s48, s2, 0x12000
	s_addc_u32 s49, s3, 0
	s_mov_b32 m0, s70
	s_nop 0
	global_load_lds_dwordx4 v154, s[48:49]
	s_and_b64 vcc, exec, s[46:47]
	s_cbranch_vccz .LBB0_1512
	s_waitcnt vmcnt(24)
	s_cbranch_execnz .LBB0_1504

.LBB0_1505:
	ds_read_b128 v[128:131], v156
	ds_read_b128 v[132:135], v156 offset:1024
	ds_read_b128 v[136:139], v156 offset:2048
	ds_read_b128 v[140:143], v156 offset:3072
	ds_read_b128 v[146:149], v157
	ds_read_b128 v[162:165], v157 offset:1024
	ds_read_b128 v[166:169], v157 offset:2048
	ds_read_b128 v[170:173], v157 offset:3072
	s_add_u32 s2, s52, 0x10000
	s_addc_u32 s3, s53, 0
	s_cmp_eq_u32 s96, 60
	s_cselect_b32 s58, s92, s2
	s_cselect_b32 s59, s45, s3
	s_cselect_b32 s64, s93, s54
	s_cselect_b32 s65, s43, s55
	s_add_u32 s60, s58, 0x8000
	s_addc_u32 s61, s59, 0
	ds_read_b128 v[174:177], v158
	ds_read_b128 v[178:181], v158 offset:1024
	ds_read_b128 v[182:185], v158 offset:2048
	ds_read_b128 v[186:189], v158 offset:3072
	ds_read_b128 v[190:193], v158 offset:4096
	ds_read_b128 v[194:197], v158 offset:5120
	ds_read_b128 v[198:201], v158 offset:6144
	ds_read_b128 v[202:205], v158 offset:7168
	s_add_u32 s12, s52, 0xc000
	s_addc_u32 s13, s53, 0
	s_mov_b32 m0, s81
	s_nop 0
	global_load_lds_dwordx4 v154, s[12:13]
	s_add_u32 s12, s52, 0xe000
	s_addc_u32 s13, s53, 0
	s_mov_b32 m0, s82
	s_nop 0
	global_load_lds_dwordx4 v154, s[12:13]
	s_waitcnt vmcnt(8)
	s_waitcnt lgkmcnt(0)
	s_add_u32 s52, s64, 0x8000
	s_addc_u32 s53, s65, 0
	s_barrier
	s_setprio 1
	s_waitcnt lgkmcnt(7)
	s_waitcnt lgkmcnt(0)
	v_mfma_f32_16x16x32_bf16 v[116:119], v[128:131], v[174:177], v[116:119]
	v_mfma_f32_16x16x32_bf16 v[116:119], v[132:135], v[178:181], v[116:119]
	v_mfma_f32_16x16x32_bf16 v[112:115], v[136:139], v[174:177], v[112:115]
	v_mfma_f32_16x16x32_bf16 v[112:115], v[140:143], v[178:181], v[112:115]
	v_mfma_f32_16x16x32_bf16 v[96:99], v[136:139], v[182:185], v[96:99]
	v_mfma_f32_16x16x32_bf16 v[96:99], v[140:143], v[186:189], v[96:99]
	v_mfma_f32_16x16x32_bf16 v[100:103], v[128:131], v[182:185], v[100:103]
	v_mfma_f32_16x16x32_bf16 v[100:103], v[132:135], v[186:189], v[100:103]
	v_mfma_f32_16x16x32_bf16 v[92:95], v[128:131], v[190:193], v[92:95]
	v_mfma_f32_16x16x32_bf16 v[92:95], v[132:135], v[194:197], v[92:95]
	v_mfma_f32_16x16x32_bf16 v[88:91], v[136:139], v[190:193], v[88:91]
	v_mfma_f32_16x16x32_bf16 v[88:91], v[140:143], v[194:197], v[88:91]
	v_mfma_f32_16x16x32_bf16 v[72:75], v[136:139], v[198:201], v[72:75]
	v_mfma_f32_16x16x32_bf16 v[72:75], v[140:143], v[202:205], v[72:75]
	v_mfma_f32_16x16x32_bf16 v[76:79], v[128:131], v[198:201], v[76:79]
	v_mfma_f32_16x16x32_bf16 v[76:79], v[132:135], v[202:205], v[76:79]
	s_setprio 0
	s_setprio 1
	s_waitcnt lgkmcnt(0)
	v_mfma_f32_16x16x32_bf16 v[124:127], v[146:149], v[174:177], v[124:127]
	v_mfma_f32_16x16x32_bf16 v[124:127], v[162:165], v[178:181], v[124:127]
	v_mfma_f32_16x16x32_bf16 v[120:123], v[166:169], v[174:177], v[120:123]
	v_mfma_f32_16x16x32_bf16 v[120:123], v[170:173], v[178:181], v[120:123]
	v_mfma_f32_16x16x32_bf16 v[104:107], v[166:169], v[182:185], v[104:107]
	v_mfma_f32_16x16x32_bf16 v[104:107], v[170:173], v[186:189], v[104:107]
	v_mfma_f32_16x16x32_bf16 v[108:111], v[146:149], v[182:185], v[108:111]
	v_mfma_f32_16x16x32_bf16 v[108:111], v[162:165], v[186:189], v[108:111]
	v_mfma_f32_16x16x32_bf16 v[84:87], v[146:149], v[190:193], v[84:87]
	v_mfma_f32_16x16x32_bf16 v[84:87], v[162:165], v[194:197], v[84:87]
	v_mfma_f32_16x16x32_bf16 v[80:83], v[166:169], v[190:193], v[80:83]
	v_mfma_f32_16x16x32_bf16 v[80:83], v[170:173], v[194:197], v[80:83]
	v_mfma_f32_16x16x32_bf16 v[64:67], v[166:169], v[198:201], v[64:67]
	v_mfma_f32_16x16x32_bf16 v[64:67], v[170:173], v[202:205], v[64:67]
	v_mfma_f32_16x16x32_bf16 v[68:71], v[146:149], v[198:201], v[68:71]
	v_mfma_f32_16x16x32_bf16 v[68:71], v[162:165], v[202:205], v[68:71]
	s_setprio 0
	s_barrier
	s_add_u32 s12, s64, 0x2000
	ds_read_b128 v[174:177], v158 offset:16384
	ds_read_b128 v[178:181], v158 offset:17408
	ds_read_b128 v[182:185], v158 offset:18432
	ds_read_b128 v[186:189], v158 offset:19456
	ds_read_b128 v[190:193], v158 offset:20480
	ds_read_b128 v[194:197], v158 offset:21504
	ds_read_b128 v[198:201], v158 offset:22528
	ds_read_b128 v[202:205], v158 offset:23552
	s_mov_b32 m0, s57
	s_nop 0
	global_load_lds_dwordx4 v154, s[64:65]
	s_addc_u32 s13, s65, 0
	s_mov_b32 m0, s67
	s_nop 0
	global_load_lds_dwordx4 v154, s[12:13]
	s_add_u32 s12, s64, 0x4000
	s_addc_u32 s13, s65, 0
	s_mov_b32 m0, s68
	s_nop 0
	global_load_lds_dwordx4 v154, s[12:13]
	s_add_u32 s12, s64, 0x6000
	s_addc_u32 s13, s65, 0
	s_mov_b32 m0, s69
	s_nop 0
	global_load_lds_dwordx4 v154, s[12:13]
	s_add_u32 s12, s58, 0x2000
	s_mov_b32 m0, s66
	s_nop 0
	global_load_lds_dwordx4 v154, s[58:59]
	s_addc_u32 s13, s59, 0
	s_mov_b32 m0, s70
	s_nop 0
	global_load_lds_dwordx4 v154, s[12:13]
	s_waitcnt vmcnt(8)
	s_waitcnt lgkmcnt(0)
	s_barrier
	s_setprio 1
	s_waitcnt lgkmcnt(7)
	s_waitcnt lgkmcnt(0)
	v_mfma_f32_16x16x32_bf16 v[60:63], v[128:131], v[174:177], v[60:63]
	v_mfma_f32_16x16x32_bf16 v[60:63], v[132:135], v[178:181], v[60:63]
	v_mfma_f32_16x16x32_bf16 v[56:59], v[136:139], v[174:177], v[56:59]
	v_mfma_f32_16x16x32_bf16 v[56:59], v[140:143], v[178:181], v[56:59]
	v_mfma_f32_16x16x32_bf16 v[40:43], v[136:139], v[182:185], v[40:43]
	v_mfma_f32_16x16x32_bf16 v[40:43], v[140:143], v[186:189], v[40:43]
	v_mfma_f32_16x16x32_bf16 v[44:47], v[128:131], v[182:185], v[44:47]
	v_mfma_f32_16x16x32_bf16 v[44:47], v[132:135], v[186:189], v[44:47]
	v_mfma_f32_16x16x32_bf16 v[28:31], v[128:131], v[190:193], v[28:31]
	v_mfma_f32_16x16x32_bf16 v[28:31], v[132:135], v[194:197], v[28:31]
	v_mfma_f32_16x16x32_bf16 v[24:27], v[136:139], v[190:193], v[24:27]
	v_mfma_f32_16x16x32_bf16 v[24:27], v[140:143], v[194:197], v[24:27]
	v_mfma_f32_16x16x32_bf16 v[8:11], v[136:139], v[198:201], v[8:11]
	v_mfma_f32_16x16x32_bf16 v[8:11], v[140:143], v[202:205], v[8:11]
	v_mfma_f32_16x16x32_bf16 v[12:15], v[128:131], v[198:201], v[12:15]
	v_mfma_f32_16x16x32_bf16 v[12:15], v[132:135], v[202:205], v[12:15]
	s_setprio 0
	s_setprio 1
	s_waitcnt lgkmcnt(0)
	v_mfma_f32_16x16x32_bf16 v[52:55], v[146:149], v[174:177], v[52:55]
	v_mfma_f32_16x16x32_bf16 v[52:55], v[162:165], v[178:181], v[52:55]
	v_mfma_f32_16x16x32_bf16 v[48:51], v[166:169], v[174:177], v[48:51]
	v_mfma_f32_16x16x32_bf16 v[48:51], v[170:173], v[178:181], v[48:51]
	v_mfma_f32_16x16x32_bf16 v[32:35], v[166:169], v[182:185], v[32:35]
	v_mfma_f32_16x16x32_bf16 v[32:35], v[170:173], v[186:189], v[32:35]
	v_mfma_f32_16x16x32_bf16 v[36:39], v[146:149], v[182:185], v[36:39]
	v_mfma_f32_16x16x32_bf16 v[36:39], v[162:165], v[186:189], v[36:39]
	v_mfma_f32_16x16x32_bf16 v[20:23], v[146:149], v[190:193], v[20:23]
	v_mfma_f32_16x16x32_bf16 v[20:23], v[162:165], v[194:197], v[20:23]
	v_mfma_f32_16x16x32_bf16 v[16:19], v[166:169], v[190:193], v[16:19]
	v_mfma_f32_16x16x32_bf16 v[16:19], v[170:173], v[194:197], v[16:19]
	v_mfma_f32_16x16x32_bf16 v[0:3], v[166:169], v[198:201], v[0:3]
	v_mfma_f32_16x16x32_bf16 v[0:3], v[170:173], v[202:205], v[0:3]
	v_mfma_f32_16x16x32_bf16 v[4:7], v[146:149], v[198:201], v[4:7]
	v_mfma_f32_16x16x32_bf16 v[4:7], v[162:165], v[202:205], v[4:7]
	s_setprio 0
	s_barrier
	ds_read_b128 v[128:131], v144
	ds_read_b128 v[132:135], v144 offset:1024
	ds_read_b128 v[136:139], v144 offset:2048
	ds_read_b128 v[140:143], v144 offset:3072
	ds_read_b128 v[146:149], v150
	ds_read_b128 v[162:165], v150 offset:1024
	ds_read_b128 v[166:169], v150 offset:2048
	ds_read_b128 v[170:173], v150 offset:3072
	ds_read_b128 v[174:177], v158 offset:32768
	ds_read_b128 v[178:181], v158 offset:33792
	ds_read_b128 v[182:185], v158 offset:34816
	ds_read_b128 v[186:189], v158 offset:35840
	ds_read_b128 v[190:193], v158 offset:36864
	ds_read_b128 v[194:197], v158 offset:37888
	ds_read_b128 v[198:201], v158 offset:38912
	ds_read_b128 v[202:205], v158 offset:39936
	s_add_u32 s12, s58, 0x4000
	s_addc_u32 s13, s59, 0
	s_mov_b32 m0, s71
	s_nop 0
	global_load_lds_dwordx4 v154, s[12:13]
	s_add_u32 s12, s58, 0x6000
	s_addc_u32 s13, s59, 0
	s_mov_b32 m0, s72
	s_nop 0
	global_load_lds_dwordx4 v154, s[12:13]
	s_waitcnt vmcnt(8)
	s_waitcnt lgkmcnt(0)
	s_barrier
	s_setprio 1
	s_waitcnt lgkmcnt(7)
	s_waitcnt lgkmcnt(0)
	v_mfma_f32_16x16x32_bf16 v[116:119], v[128:131], v[174:177], v[116:119]
	v_mfma_f32_16x16x32_bf16 v[116:119], v[132:135], v[178:181], v[116:119]
	v_mfma_f32_16x16x32_bf16 v[112:115], v[136:139], v[174:177], v[112:115]
	v_mfma_f32_16x16x32_bf16 v[112:115], v[140:143], v[178:181], v[112:115]
	v_mfma_f32_16x16x32_bf16 v[96:99], v[136:139], v[182:185], v[96:99]
	v_mfma_f32_16x16x32_bf16 v[96:99], v[140:143], v[186:189], v[96:99]
	v_mfma_f32_16x16x32_bf16 v[100:103], v[128:131], v[182:185], v[100:103]
	v_mfma_f32_16x16x32_bf16 v[100:103], v[132:135], v[186:189], v[100:103]
	v_mfma_f32_16x16x32_bf16 v[92:95], v[128:131], v[190:193], v[92:95]
	v_mfma_f32_16x16x32_bf16 v[92:95], v[132:135], v[194:197], v[92:95]
	v_mfma_f32_16x16x32_bf16 v[88:91], v[136:139], v[190:193], v[88:91]
	v_mfma_f32_16x16x32_bf16 v[88:91], v[140:143], v[194:197], v[88:91]
	v_mfma_f32_16x16x32_bf16 v[72:75], v[136:139], v[198:201], v[72:75]
	v_mfma_f32_16x16x32_bf16 v[72:75], v[140:143], v[202:205], v[72:75]
	v_mfma_f32_16x16x32_bf16 v[76:79], v[128:131], v[198:201], v[76:79]
	v_mfma_f32_16x16x32_bf16 v[76:79], v[132:135], v[202:205], v[76:79]
	s_setprio 0
	s_setprio 1
	s_waitcnt lgkmcnt(0)
	v_mfma_f32_16x16x32_bf16 v[124:127], v[146:149], v[174:177], v[124:127]
	v_mfma_f32_16x16x32_bf16 v[124:127], v[162:165], v[178:181], v[124:127]
	v_mfma_f32_16x16x32_bf16 v[120:123], v[166:169], v[174:177], v[120:123]
	v_mfma_f32_16x16x32_bf16 v[120:123], v[170:173], v[178:181], v[120:123]
	v_mfma_f32_16x16x32_bf16 v[104:107], v[166:169], v[182:185], v[104:107]
	v_mfma_f32_16x16x32_bf16 v[104:107], v[170:173], v[186:189], v[104:107]
	v_mfma_f32_16x16x32_bf16 v[108:111], v[146:149], v[182:185], v[108:111]
	v_mfma_f32_16x16x32_bf16 v[108:111], v[162:165], v[186:189], v[108:111]
	v_mfma_f32_16x16x32_bf16 v[84:87], v[146:149], v[190:193], v[84:87]
	v_mfma_f32_16x16x32_bf16 v[84:87], v[162:165], v[194:197], v[84:87]
	v_mfma_f32_16x16x32_bf16 v[80:83], v[166:169], v[190:193], v[80:83]
	v_mfma_f32_16x16x32_bf16 v[80:83], v[170:173], v[194:197], v[80:83]
	v_mfma_f32_16x16x32_bf16 v[64:67], v[166:169], v[198:201], v[64:67]
	v_mfma_f32_16x16x32_bf16 v[64:67], v[170:173], v[202:205], v[64:67]
	v_mfma_f32_16x16x32_bf16 v[68:71], v[146:149], v[198:201], v[68:71]
	v_mfma_f32_16x16x32_bf16 v[68:71], v[162:165], v[202:205], v[68:71]
	s_setprio 0
	s_barrier
	s_add_u32 s12, s64, 0xa000
	ds_read_b128 v[174:177], v158 offset:49152
	ds_read_b128 v[178:181], v158 offset:50176
	ds_read_b128 v[182:185], v158 offset:51200
	ds_read_b128 v[186:189], v158 offset:52224
	ds_read_b128 v[190:193], v158 offset:53248
	ds_read_b128 v[194:197], v158 offset:54272
	ds_read_b128 v[198:201], v158 offset:55296
	ds_read_b128 v[202:205], v158 offset:56320
	s_mov_b32 m0, s75
	s_nop 0
	global_load_lds_dwordx4 v154, s[52:53]
	s_addc_u32 s13, s65, 0
	s_mov_b32 m0, s76
	s_nop 0
	global_load_lds_dwordx4 v154, s[12:13]
	s_add_u32 s12, s64, 0xc000
	s_addc_u32 s13, s65, 0
	s_mov_b32 m0, s79
	s_nop 0
	global_load_lds_dwordx4 v154, s[12:13]
	s_add_u32 s12, s64, 0xe000
	s_addc_u32 s13, s65, 0
	s_mov_b32 m0, s80
	s_nop 0
	global_load_lds_dwordx4 v154, s[12:13]
	s_add_u32 s12, s58, 0xa000
	s_mov_b32 m0, s77
	s_nop 0
	global_load_lds_dwordx4 v154, s[60:61]
	s_addc_u32 s13, s59, 0
	s_mov_b32 m0, s78
	s_nop 0
	global_load_lds_dwordx4 v154, s[12:13]
	s_waitcnt vmcnt(8)
	s_waitcnt lgkmcnt(0)
	s_barrier
	s_setprio 1
	s_waitcnt lgkmcnt(7)
	s_waitcnt lgkmcnt(0)
	v_mfma_f32_16x16x32_bf16 v[60:63], v[128:131], v[174:177], v[60:63]
	v_mfma_f32_16x16x32_bf16 v[60:63], v[132:135], v[178:181], v[60:63]
	v_mfma_f32_16x16x32_bf16 v[56:59], v[136:139], v[174:177], v[56:59]
	v_mfma_f32_16x16x32_bf16 v[56:59], v[140:143], v[178:181], v[56:59]
	v_mfma_f32_16x16x32_bf16 v[40:43], v[136:139], v[182:185], v[40:43]
	v_mfma_f32_16x16x32_bf16 v[40:43], v[140:143], v[186:189], v[40:43]
	v_mfma_f32_16x16x32_bf16 v[44:47], v[128:131], v[182:185], v[44:47]
	v_mfma_f32_16x16x32_bf16 v[44:47], v[132:135], v[186:189], v[44:47]
	v_mfma_f32_16x16x32_bf16 v[28:31], v[128:131], v[190:193], v[28:31]
	v_mfma_f32_16x16x32_bf16 v[28:31], v[132:135], v[194:197], v[28:31]
	v_mfma_f32_16x16x32_bf16 v[24:27], v[136:139], v[190:193], v[24:27]
	v_mfma_f32_16x16x32_bf16 v[24:27], v[140:143], v[194:197], v[24:27]
	v_mfma_f32_16x16x32_bf16 v[8:11], v[136:139], v[198:201], v[8:11]
	v_mfma_f32_16x16x32_bf16 v[8:11], v[140:143], v[202:205], v[8:11]
	v_mfma_f32_16x16x32_bf16 v[12:15], v[128:131], v[198:201], v[12:15]
	v_mfma_f32_16x16x32_bf16 v[12:15], v[132:135], v[202:205], v[12:15]
	s_setprio 0
	s_setprio 1
	s_waitcnt lgkmcnt(0)
	v_mfma_f32_16x16x32_bf16 v[52:55], v[146:149], v[174:177], v[52:55]
	v_mfma_f32_16x16x32_bf16 v[52:55], v[162:165], v[178:181], v[52:55]
	v_mfma_f32_16x16x32_bf16 v[48:51], v[166:169], v[174:177], v[48:51]
	v_mfma_f32_16x16x32_bf16 v[48:51], v[170:173], v[178:181], v[48:51]
	v_mfma_f32_16x16x32_bf16 v[32:35], v[166:169], v[182:185], v[32:35]
	v_mfma_f32_16x16x32_bf16 v[32:35], v[170:173], v[186:189], v[32:35]
	v_mfma_f32_16x16x32_bf16 v[36:39], v[146:149], v[182:185], v[36:39]
	v_mfma_f32_16x16x32_bf16 v[36:39], v[162:165], v[186:189], v[36:39]
	v_mfma_f32_16x16x32_bf16 v[20:23], v[146:149], v[190:193], v[20:23]
	v_mfma_f32_16x16x32_bf16 v[20:23], v[162:165], v[194:197], v[20:23]
	v_mfma_f32_16x16x32_bf16 v[16:19], v[166:169], v[190:193], v[16:19]
	v_mfma_f32_16x16x32_bf16 v[16:19], v[170:173], v[194:197], v[16:19]
	v_mfma_f32_16x16x32_bf16 v[0:3], v[166:169], v[198:201], v[0:3]
	v_mfma_f32_16x16x32_bf16 v[0:3], v[170:173], v[202:205], v[0:3]
	v_mfma_f32_16x16x32_bf16 v[4:7], v[146:149], v[198:201], v[4:7]
	v_mfma_f32_16x16x32_bf16 v[4:7], v[162:165], v[202:205], v[4:7]
	s_setprio 0
	s_barrier
	s_add_i32 s96, s96, 2
	s_add_u32 s54, s54, 0x10000
	s_addc_u32 s55, s55, 0
	s_cmp_gt_u32 s96, 61
	s_mov_b64 s[52:53], s[2:3]
	s_cbranch_scc0 .LBB0_1505
	s_and_b64 vcc, exec, s[40:41]
	s_cbranch_vccz .LBB0_1508
	s_barrier

.LBB0_1535:
	s_add_u32 s44, s46, 0x10000
	s_waitcnt lgkmcnt(0)
	s_addc_u32 s45, s47, 0
	s_add_u32 s48, s2, 0x10000
	s_addc_u32 s49, s3, 0
	s_barrier
	s_setprio 1
	s_waitcnt lgkmcnt(7)
	s_waitcnt lgkmcnt(0)
	v_mfma_f32_16x16x32_bf16 v[32:35], v[16:19], v[72:75], 0
	v_mfma_f32_16x16x32_bf16 v[32:35], v[20:23], v[76:79], v[32:35]
	v_mfma_f32_16x16x32_bf16 v[36:39], v[24:27], v[72:75], 0
	v_mfma_f32_16x16x32_bf16 v[36:39], v[28:31], v[76:79], v[36:39]
	v_mfma_f32_16x16x32_bf16 v[44:47], v[24:27], v[80:83], 0
	v_mfma_f32_16x16x32_bf16 v[44:47], v[28:31], v[88:91], v[44:47]
	v_mfma_f32_16x16x32_bf16 v[40:43], v[16:19], v[80:83], 0
	v_mfma_f32_16x16x32_bf16 v[40:43], v[20:23], v[88:91], v[40:43]
	v_mfma_f32_16x16x32_bf16 v[48:51], v[16:19], v[92:95], 0
	v_mfma_f32_16x16x32_bf16 v[48:51], v[20:23], v[96:99], v[48:51]
	v_mfma_f32_16x16x32_bf16 v[52:55], v[24:27], v[92:95], 0
	v_mfma_f32_16x16x32_bf16 v[52:55], v[28:31], v[96:99], v[52:55]
	v_mfma_f32_16x16x32_bf16 v[60:63], v[24:27], v[68:71], 0
	v_mfma_f32_16x16x32_bf16 v[60:63], v[28:31], v[84:87], v[60:63]
	v_mfma_f32_16x16x32_bf16 v[56:59], v[16:19], v[68:71], 0
	v_mfma_f32_16x16x32_bf16 v[56:59], v[20:23], v[84:87], v[56:59]
	s_setprio 0
	s_setprio 1
	v_mfma_f32_16x16x32_bf16 v[64:67], v[0:3], v[72:75], 0
	v_mfma_f32_16x16x32_bf16 v[72:75], v[8:11], v[72:75], 0
	v_mfma_f32_16x16x32_bf16 v[64:67], v[4:7], v[76:79], v[64:67]
	v_mfma_f32_16x16x32_bf16 v[72:75], v[12:15], v[76:79], v[72:75]
	v_mfma_f32_16x16x32_bf16 v[76:79], v[0:3], v[80:83], 0
	v_mfma_f32_16x16x32_bf16 v[80:83], v[8:11], v[80:83], 0
	v_mfma_f32_16x16x32_bf16 v[76:79], v[4:7], v[88:91], v[76:79]
	v_mfma_f32_16x16x32_bf16 v[80:83], v[12:15], v[88:91], v[80:83]
	v_mfma_f32_16x16x32_bf16 v[88:91], v[0:3], v[92:95], 0
	v_mfma_f32_16x16x32_bf16 v[92:95], v[8:11], v[92:95], 0
	v_mfma_f32_16x16x32_bf16 v[88:91], v[4:7], v[96:99], v[88:91]
	v_mfma_f32_16x16x32_bf16 v[92:95], v[12:15], v[96:99], v[92:95]
	v_mfma_f32_16x16x32_bf16 v[96:99], v[0:3], v[68:71], 0
	v_mfma_f32_16x16x32_bf16 v[68:71], v[8:11], v[68:71], 0
	v_mfma_f32_16x16x32_bf16 v[128:131], v[4:7], v[84:87], v[96:99]
	v_mfma_f32_16x16x32_bf16 v[132:135], v[12:15], v[84:87], v[68:71]
	s_setprio 0
	s_barrier
	ds_read_b128 v[112:115], v140 offset:16384
	ds_read_b128 v[116:119], v140 offset:17408
	ds_read_b128 v[104:107], v140 offset:18432
	ds_read_b128 v[108:111], v140 offset:19456
	ds_read_b128 v[96:99], v140 offset:20480
	ds_read_b128 v[100:103], v140 offset:21504
	ds_read_b128 v[68:71], v140 offset:22528
	ds_read_b128 v[84:87], v140 offset:23552
	s_mov_b32 m0, s41
	s_nop 0
	global_load_lds_dwordx4 v136, s[48:49]
	s_add_u32 s48, s2, 0x12000
	s_addc_u32 s49, s3, 0
	s_mov_b32 m0, s59
	s_nop 0
	global_load_lds_dwordx4 v136, s[48:49]
	s_add_u32 s48, s2, 0x14000
	s_addc_u32 s49, s3, 0
	s_mov_b32 m0, s60
	s_nop 0
	global_load_lds_dwordx4 v136, s[48:49]
	s_add_u32 s48, s2, 0x16000
	s_addc_u32 s49, s3, 0
	s_mov_b32 m0, s61
	s_nop 0
	global_load_lds_dwordx4 v136, s[48:49]
	s_nop 0
	s_mov_b32 m0, s58
	s_nop 0
	global_load_lds_dwordx4 v136, s[44:45]
	s_add_u32 s44, s46, 0x12000
	s_addc_u32 s45, s47, 0
	s_mov_b32 m0, s62
	s_nop 0
	global_load_lds_dwordx4 v136, s[44:45]
	s_and_b64 vcc, exec, s[42:43]
	s_cbranch_vccz .LBB0_1546
	s_waitcnt vmcnt(24)
	s_cbranch_execnz .LBB0_1538

.LBB0_1539:
	ds_read_b128 v[128:131], v138
	ds_read_b128 v[132:135], v138 offset:1024
	ds_read_b128 v[144:147], v138 offset:2048
	ds_read_b128 v[148:151], v138 offset:3072
	ds_read_b128 v[152:155], v139
	ds_read_b128 v[156:159], v139 offset:1024
	ds_read_b128 v[160:163], v139 offset:2048
	ds_read_b128 v[164:167], v139 offset:3072
	s_add_u32 s2, s52, 0x10000
	s_addc_u32 s3, s53, 0
	s_cmp_eq_u32 s83, 60
	s_cselect_b32 s46, s79, s2
	s_cselect_b32 s47, s39, s3
	s_cselect_b32 s56, s80, s81
	s_cselect_b32 s57, s15, s82
	s_add_u32 s48, s46, 0x8000
	s_addc_u32 s49, s47, 0
	ds_read_b128 v[168:171], v140
	ds_read_b128 v[172:175], v140 offset:1024
	ds_read_b128 v[176:179], v140 offset:2048
	ds_read_b128 v[180:183], v140 offset:3072
	ds_read_b128 v[184:187], v140 offset:4096
	ds_read_b128 v[188:191], v140 offset:5120
	ds_read_b128 v[192:195], v140 offset:6144
	ds_read_b128 v[196:199], v140 offset:7168
	s_add_u32 s88, s52, 0xc000
	s_addc_u32 s89, s53, 0
	s_mov_b32 m0, s74
	s_nop 0
	global_load_lds_dwordx4 v136, s[88:89]
	s_add_u32 s52, s52, 0xe000
	s_addc_u32 s53, s53, 0
	s_mov_b32 m0, s75
	s_nop 0
	global_load_lds_dwordx4 v136, s[52:53]
	s_waitcnt vmcnt(8)
	s_waitcnt lgkmcnt(0)
	s_add_u32 s52, s56, 0x8000
	s_addc_u32 s53, s57, 0
	s_barrier
	s_setprio 1
	s_waitcnt lgkmcnt(7)
	s_waitcnt lgkmcnt(0)
	v_mfma_f32_16x16x32_bf16 v[120:123], v[128:131], v[168:171], v[120:123]
	v_mfma_f32_16x16x32_bf16 v[120:123], v[132:135], v[172:175], v[120:123]
	v_mfma_f32_16x16x32_bf16 v[112:115], v[144:147], v[168:171], v[112:115]
	v_mfma_f32_16x16x32_bf16 v[112:115], v[148:151], v[172:175], v[112:115]
	v_mfma_f32_16x16x32_bf16 v[96:99], v[144:147], v[176:179], v[96:99]
	v_mfma_f32_16x16x32_bf16 v[96:99], v[148:151], v[180:183], v[96:99]
	v_mfma_f32_16x16x32_bf16 v[104:107], v[128:131], v[176:179], v[104:107]
	v_mfma_f32_16x16x32_bf16 v[104:107], v[132:135], v[180:183], v[104:107]
	v_mfma_f32_16x16x32_bf16 v[84:87], v[128:131], v[184:187], v[84:87]
	v_mfma_f32_16x16x32_bf16 v[84:87], v[132:135], v[188:191], v[84:87]
	v_mfma_f32_16x16x32_bf16 v[68:71], v[144:147], v[184:187], v[68:71]
	v_mfma_f32_16x16x32_bf16 v[68:71], v[148:151], v[188:191], v[68:71]
	v_mfma_f32_16x16x32_bf16 v[36:39], v[144:147], v[192:195], v[36:39]
	v_mfma_f32_16x16x32_bf16 v[36:39], v[148:151], v[196:199], v[36:39]
	v_mfma_f32_16x16x32_bf16 v[52:55], v[128:131], v[192:195], v[52:55]
	v_mfma_f32_16x16x32_bf16 v[52:55], v[132:135], v[196:199], v[52:55]
	s_setprio 0
	s_setprio 1
	s_waitcnt lgkmcnt(0)
	v_mfma_f32_16x16x32_bf16 v[124:127], v[152:155], v[168:171], v[124:127]
	v_mfma_f32_16x16x32_bf16 v[124:127], v[156:159], v[172:175], v[124:127]
	v_mfma_f32_16x16x32_bf16 v[116:119], v[160:163], v[168:171], v[116:119]
	v_mfma_f32_16x16x32_bf16 v[116:119], v[164:167], v[172:175], v[116:119]
	v_mfma_f32_16x16x32_bf16 v[100:103], v[160:163], v[176:179], v[100:103]
	v_mfma_f32_16x16x32_bf16 v[100:103], v[164:167], v[180:183], v[100:103]
	v_mfma_f32_16x16x32_bf16 v[108:111], v[152:155], v[176:179], v[108:111]
	v_mfma_f32_16x16x32_bf16 v[108:111], v[156:159], v[180:183], v[108:111]
	v_mfma_f32_16x16x32_bf16 v[88:91], v[152:155], v[184:187], v[88:91]
	v_mfma_f32_16x16x32_bf16 v[88:91], v[156:159], v[188:191], v[88:91]
	v_mfma_f32_16x16x32_bf16 v[72:75], v[160:163], v[184:187], v[72:75]
	v_mfma_f32_16x16x32_bf16 v[72:75], v[164:167], v[188:191], v[72:75]
	v_mfma_f32_16x16x32_bf16 v[40:43], v[160:163], v[192:195], v[40:43]
	v_mfma_f32_16x16x32_bf16 v[40:43], v[164:167], v[196:199], v[40:43]
	v_mfma_f32_16x16x32_bf16 v[56:59], v[152:155], v[192:195], v[56:59]
	v_mfma_f32_16x16x32_bf16 v[56:59], v[156:159], v[196:199], v[56:59]
	s_setprio 0
	s_barrier
	s_add_u32 s88, s56, 0x2000
	ds_read_b128 v[168:171], v140 offset:16384
	ds_read_b128 v[172:175], v140 offset:17408
	ds_read_b128 v[176:179], v140 offset:18432
	ds_read_b128 v[180:183], v140 offset:19456
	ds_read_b128 v[184:187], v140 offset:20480
	ds_read_b128 v[188:191], v140 offset:21504
	ds_read_b128 v[192:195], v140 offset:22528
	ds_read_b128 v[196:199], v140 offset:23552
	s_mov_b32 m0, s41
	s_nop 0
	global_load_lds_dwordx4 v136, s[56:57]
	s_addc_u32 s89, s57, 0
	s_mov_b32 m0, s59
	s_nop 0
	global_load_lds_dwordx4 v136, s[88:89]
	s_add_u32 s88, s56, 0x4000
	s_addc_u32 s89, s57, 0
	s_mov_b32 m0, s60
	s_nop 0
	global_load_lds_dwordx4 v136, s[88:89]
	s_add_u32 s88, s56, 0x6000
	s_addc_u32 s89, s57, 0
	s_mov_b32 m0, s61
	s_nop 0
	global_load_lds_dwordx4 v136, s[88:89]
	s_add_u32 s88, s46, 0x2000
	s_mov_b32 m0, s58
	s_nop 0
	global_load_lds_dwordx4 v136, s[46:47]
	s_addc_u32 s89, s47, 0
	s_mov_b32 m0, s62
	s_nop 0
	global_load_lds_dwordx4 v136, s[88:89]
	s_waitcnt vmcnt(8)
	s_waitcnt lgkmcnt(0)
	s_barrier
	s_setprio 1
	s_waitcnt lgkmcnt(7)
	s_waitcnt lgkmcnt(0)
	v_mfma_f32_16x16x32_bf16 v[92:95], v[128:131], v[168:171], v[92:95]
	v_mfma_f32_16x16x32_bf16 v[92:95], v[132:135], v[172:175], v[92:95]
	v_mfma_f32_16x16x32_bf16 v[80:83], v[144:147], v[168:171], v[80:83]
	v_mfma_f32_16x16x32_bf16 v[80:83], v[148:151], v[172:175], v[80:83]
	v_mfma_f32_16x16x32_bf16 v[48:51], v[144:147], v[176:179], v[48:51]
	v_mfma_f32_16x16x32_bf16 v[48:51], v[148:151], v[180:183], v[48:51]
	v_mfma_f32_16x16x32_bf16 v[60:63], v[128:131], v[176:179], v[60:63]
	v_mfma_f32_16x16x32_bf16 v[60:63], v[132:135], v[180:183], v[60:63]
	v_mfma_f32_16x16x32_bf16 v[28:31], v[128:131], v[184:187], v[28:31]
	v_mfma_f32_16x16x32_bf16 v[28:31], v[132:135], v[188:191], v[28:31]
	v_mfma_f32_16x16x32_bf16 v[24:27], v[144:147], v[184:187], v[24:27]
	v_mfma_f32_16x16x32_bf16 v[24:27], v[148:151], v[188:191], v[24:27]
	v_mfma_f32_16x16x32_bf16 v[8:11], v[144:147], v[192:195], v[8:11]
	v_mfma_f32_16x16x32_bf16 v[8:11], v[148:151], v[196:199], v[8:11]
	v_mfma_f32_16x16x32_bf16 v[12:15], v[128:131], v[192:195], v[12:15]
	v_mfma_f32_16x16x32_bf16 v[12:15], v[132:135], v[196:199], v[12:15]
	s_setprio 0
	s_setprio 1
	s_waitcnt lgkmcnt(0)
	v_mfma_f32_16x16x32_bf16 v[76:79], v[152:155], v[168:171], v[76:79]
	v_mfma_f32_16x16x32_bf16 v[76:79], v[156:159], v[172:175], v[76:79]
	v_mfma_f32_16x16x32_bf16 v[64:67], v[160:163], v[168:171], v[64:67]
	v_mfma_f32_16x16x32_bf16 v[64:67], v[164:167], v[172:175], v[64:67]
	v_mfma_f32_16x16x32_bf16 v[32:35], v[160:163], v[176:179], v[32:35]
	v_mfma_f32_16x16x32_bf16 v[32:35], v[164:167], v[180:183], v[32:35]
	v_mfma_f32_16x16x32_bf16 v[44:47], v[152:155], v[176:179], v[44:47]
	v_mfma_f32_16x16x32_bf16 v[44:47], v[156:159], v[180:183], v[44:47]
	v_mfma_f32_16x16x32_bf16 v[20:23], v[152:155], v[184:187], v[20:23]
	v_mfma_f32_16x16x32_bf16 v[20:23], v[156:159], v[188:191], v[20:23]
	v_mfma_f32_16x16x32_bf16 v[16:19], v[160:163], v[184:187], v[16:19]
	v_mfma_f32_16x16x32_bf16 v[16:19], v[164:167], v[188:191], v[16:19]
	v_mfma_f32_16x16x32_bf16 v[0:3], v[160:163], v[192:195], v[0:3]
	v_mfma_f32_16x16x32_bf16 v[0:3], v[164:167], v[196:199], v[0:3]
	v_mfma_f32_16x16x32_bf16 v[4:7], v[152:155], v[192:195], v[4:7]
	v_mfma_f32_16x16x32_bf16 v[4:7], v[156:159], v[196:199], v[4:7]
	s_setprio 0
	s_barrier
	ds_read_b128 v[128:131], v141
	ds_read_b128 v[132:135], v141 offset:1024
	ds_read_b128 v[144:147], v141 offset:2048
	ds_read_b128 v[148:151], v141 offset:3072
	ds_read_b128 v[152:155], v142
	ds_read_b128 v[156:159], v142 offset:1024
	ds_read_b128 v[160:163], v142 offset:2048
	ds_read_b128 v[164:167], v142 offset:3072
	ds_read_b128 v[168:171], v140 offset:32768
	ds_read_b128 v[172:175], v140 offset:33792
	ds_read_b128 v[176:179], v140 offset:34816
	ds_read_b128 v[180:183], v140 offset:35840
	ds_read_b128 v[184:187], v140 offset:36864
	ds_read_b128 v[188:191], v140 offset:37888
	ds_read_b128 v[192:195], v140 offset:38912
	ds_read_b128 v[196:199], v140 offset:39936
	s_add_u32 s88, s46, 0x4000
	s_addc_u32 s89, s47, 0
	s_mov_b32 m0, s63
	s_nop 0
	global_load_lds_dwordx4 v136, s[88:89]
	s_add_u32 s88, s46, 0x6000
	s_addc_u32 s89, s47, 0
	s_mov_b32 m0, s64
	s_nop 0
	global_load_lds_dwordx4 v136, s[88:89]
	s_waitcnt vmcnt(8)
	s_waitcnt lgkmcnt(0)
	s_barrier
	s_setprio 1
	s_waitcnt lgkmcnt(7)
	s_waitcnt lgkmcnt(0)
	v_mfma_f32_16x16x32_bf16 v[120:123], v[128:131], v[168:171], v[120:123]
	v_mfma_f32_16x16x32_bf16 v[120:123], v[132:135], v[172:175], v[120:123]
	v_mfma_f32_16x16x32_bf16 v[112:115], v[144:147], v[168:171], v[112:115]
	v_mfma_f32_16x16x32_bf16 v[112:115], v[148:151], v[172:175], v[112:115]
	v_mfma_f32_16x16x32_bf16 v[96:99], v[144:147], v[176:179], v[96:99]
	v_mfma_f32_16x16x32_bf16 v[96:99], v[148:151], v[180:183], v[96:99]
	v_mfma_f32_16x16x32_bf16 v[104:107], v[128:131], v[176:179], v[104:107]
	v_mfma_f32_16x16x32_bf16 v[104:107], v[132:135], v[180:183], v[104:107]
	v_mfma_f32_16x16x32_bf16 v[84:87], v[128:131], v[184:187], v[84:87]
	v_mfma_f32_16x16x32_bf16 v[84:87], v[132:135], v[188:191], v[84:87]
	v_mfma_f32_16x16x32_bf16 v[68:71], v[144:147], v[184:187], v[68:71]
	v_mfma_f32_16x16x32_bf16 v[68:71], v[148:151], v[188:191], v[68:71]
	v_mfma_f32_16x16x32_bf16 v[36:39], v[144:147], v[192:195], v[36:39]
	v_mfma_f32_16x16x32_bf16 v[36:39], v[148:151], v[196:199], v[36:39]
	v_mfma_f32_16x16x32_bf16 v[52:55], v[128:131], v[192:195], v[52:55]
	v_mfma_f32_16x16x32_bf16 v[52:55], v[132:135], v[196:199], v[52:55]
	s_setprio 0
	s_setprio 1
	s_waitcnt lgkmcnt(0)
	v_mfma_f32_16x16x32_bf16 v[124:127], v[152:155], v[168:171], v[124:127]
	v_mfma_f32_16x16x32_bf16 v[124:127], v[156:159], v[172:175], v[124:127]
	v_mfma_f32_16x16x32_bf16 v[116:119], v[160:163], v[168:171], v[116:119]
	v_mfma_f32_16x16x32_bf16 v[116:119], v[164:167], v[172:175], v[116:119]
	v_mfma_f32_16x16x32_bf16 v[100:103], v[160:163], v[176:179], v[100:103]
	v_mfma_f32_16x16x32_bf16 v[100:103], v[164:167], v[180:183], v[100:103]
	v_mfma_f32_16x16x32_bf16 v[108:111], v[152:155], v[176:179], v[108:111]
	v_mfma_f32_16x16x32_bf16 v[108:111], v[156:159], v[180:183], v[108:111]
	v_mfma_f32_16x16x32_bf16 v[88:91], v[152:155], v[184:187], v[88:91]
	v_mfma_f32_16x16x32_bf16 v[88:91], v[156:159], v[188:191], v[88:91]
	v_mfma_f32_16x16x32_bf16 v[72:75], v[160:163], v[184:187], v[72:75]
	v_mfma_f32_16x16x32_bf16 v[72:75], v[164:167], v[188:191], v[72:75]
	v_mfma_f32_16x16x32_bf16 v[40:43], v[160:163], v[192:195], v[40:43]
	v_mfma_f32_16x16x32_bf16 v[40:43], v[164:167], v[196:199], v[40:43]
	v_mfma_f32_16x16x32_bf16 v[56:59], v[152:155], v[192:195], v[56:59]
	v_mfma_f32_16x16x32_bf16 v[56:59], v[156:159], v[196:199], v[56:59]
	s_setprio 0
	s_barrier
	ds_read_b128 v[168:171], v140 offset:49152
	ds_read_b128 v[172:175], v140 offset:50176
	ds_read_b128 v[176:179], v140 offset:51200
	ds_read_b128 v[180:183], v140 offset:52224
	ds_read_b128 v[184:187], v140 offset:53248
	ds_read_b128 v[188:191], v140 offset:54272
	ds_read_b128 v[192:195], v140 offset:55296
	ds_read_b128 v[196:199], v140 offset:56320
	s_mov_b32 m0, s68
	s_nop 0
	global_load_lds_dwordx4 v136, s[52:53]
	s_add_u32 s52, s56, 0xa000
	s_addc_u32 s53, s57, 0
	s_mov_b32 m0, s69
	s_nop 0
	global_load_lds_dwordx4 v136, s[52:53]
	s_add_u32 s52, s56, 0xc000
	s_addc_u32 s53, s57, 0
	s_mov_b32 m0, s72
	s_nop 0
	global_load_lds_dwordx4 v136, s[52:53]
	s_add_u32 s52, s56, 0xe000
	s_addc_u32 s53, s57, 0
	s_mov_b32 m0, s73
	s_nop 0
	global_load_lds_dwordx4 v136, s[52:53]
	s_add_u32 s46, s46, 0xa000
	s_mov_b32 m0, s70
	s_nop 0
	global_load_lds_dwordx4 v136, s[48:49]
	s_addc_u32 s47, s47, 0
	s_mov_b32 m0, s71
	s_nop 0
	global_load_lds_dwordx4 v136, s[46:47]
	s_waitcnt vmcnt(8)
	s_waitcnt lgkmcnt(0)
	s_barrier
	s_setprio 1
	s_waitcnt lgkmcnt(7)
	s_waitcnt lgkmcnt(0)
	v_mfma_f32_16x16x32_bf16 v[92:95], v[128:131], v[168:171], v[92:95]
	v_mfma_f32_16x16x32_bf16 v[92:95], v[132:135], v[172:175], v[92:95]
	v_mfma_f32_16x16x32_bf16 v[80:83], v[144:147], v[168:171], v[80:83]
	v_mfma_f32_16x16x32_bf16 v[80:83], v[148:151], v[172:175], v[80:83]
	v_mfma_f32_16x16x32_bf16 v[48:51], v[144:147], v[176:179], v[48:51]
	v_mfma_f32_16x16x32_bf16 v[48:51], v[148:151], v[180:183], v[48:51]
	v_mfma_f32_16x16x32_bf16 v[60:63], v[128:131], v[176:179], v[60:63]
	v_mfma_f32_16x16x32_bf16 v[60:63], v[132:135], v[180:183], v[60:63]
	v_mfma_f32_16x16x32_bf16 v[28:31], v[128:131], v[184:187], v[28:31]
	v_mfma_f32_16x16x32_bf16 v[28:31], v[132:135], v[188:191], v[28:31]
	v_mfma_f32_16x16x32_bf16 v[24:27], v[144:147], v[184:187], v[24:27]
	v_mfma_f32_16x16x32_bf16 v[24:27], v[148:151], v[188:191], v[24:27]
	v_mfma_f32_16x16x32_bf16 v[8:11], v[144:147], v[192:195], v[8:11]
	v_mfma_f32_16x16x32_bf16 v[8:11], v[148:151], v[196:199], v[8:11]
	v_mfma_f32_16x16x32_bf16 v[12:15], v[128:131], v[192:195], v[12:15]
	v_mfma_f32_16x16x32_bf16 v[12:15], v[132:135], v[196:199], v[12:15]
	s_setprio 0
	s_setprio 1
	s_waitcnt lgkmcnt(0)
	v_mfma_f32_16x16x32_bf16 v[76:79], v[152:155], v[168:171], v[76:79]
	v_mfma_f32_16x16x32_bf16 v[76:79], v[156:159], v[172:175], v[76:79]
	v_mfma_f32_16x16x32_bf16 v[64:67], v[160:163], v[168:171], v[64:67]
	v_mfma_f32_16x16x32_bf16 v[64:67], v[164:167], v[172:175], v[64:67]
	v_mfma_f32_16x16x32_bf16 v[32:35], v[160:163], v[176:179], v[32:35]
	v_mfma_f32_16x16x32_bf16 v[32:35], v[164:167], v[180:183], v[32:35]
	v_mfma_f32_16x16x32_bf16 v[44:47], v[152:155], v[176:179], v[44:47]
	v_mfma_f32_16x16x32_bf16 v[44:47], v[156:159], v[180:183], v[44:47]
	v_mfma_f32_16x16x32_bf16 v[20:23], v[152:155], v[184:187], v[20:23]
	v_mfma_f32_16x16x32_bf16 v[20:23], v[156:159], v[188:191], v[20:23]
	v_mfma_f32_16x16x32_bf16 v[16:19], v[160:163], v[184:187], v[16:19]
	v_mfma_f32_16x16x32_bf16 v[16:19], v[164:167], v[188:191], v[16:19]
	v_mfma_f32_16x16x32_bf16 v[0:3], v[160:163], v[192:195], v[0:3]
	v_mfma_f32_16x16x32_bf16 v[0:3], v[164:167], v[196:199], v[0:3]
	v_mfma_f32_16x16x32_bf16 v[4:7], v[152:155], v[192:195], v[4:7]
	v_mfma_f32_16x16x32_bf16 v[4:7], v[156:159], v[196:199], v[4:7]
	s_setprio 0
	s_barrier
	s_add_i32 s83, s83, 2
	s_add_u32 s81, s81, 0x10000
	s_addc_u32 s82, s82, 0
	s_cmp_gt_u32 s83, 61
	s_mov_b64 s[52:53], s[2:3]
	s_cbranch_scc0 .LBB0_1539
	s_and_b64 vcc, exec, s[8:9]
	s_cbranch_vccz .LBB0_1542
	s_barrier

.LBB0_1675:
	ds_read_b128 v[48:51], v214
	ds_read_b128 v[64:67], v214 offset:1024
	ds_read_b128 v[80:83], v214 offset:2048
	ds_read_b128 v[92:95], v214 offset:3072
	ds_read_b128 v[104:107], v215
	ds_read_b128 v[116:119], v215 offset:1024
	ds_read_b128 v[140:143], v215 offset:2048
	ds_read_b128 v[144:147], v215 offset:3072
	s_cmp_eq_u32 s93, 4
	s_cselect_b32 s2, s89, s54
	s_cselect_b32 s3, s43, s55
	s_cselect_b32 s60, s90, s91
	s_cselect_b32 s61, s41, s92
	s_add_u32 s58, s2, 0x8000
	s_addc_u32 s59, s3, 0
	ds_read_b128 v[156:159], v216
	ds_read_b128 v[168:171], v216 offset:1024
	ds_read_b128 v[172:175], v216 offset:2048
	ds_read_b128 v[176:179], v216 offset:3072
	ds_read_b128 v[180:183], v216 offset:4096
	ds_read_b128 v[184:187], v216 offset:5120
	ds_read_b128 v[188:191], v216 offset:6144
	ds_read_b128 v[194:197], v216 offset:7168
	s_add_u32 s52, s54, 0xffffc000
	s_addc_u32 s53, s55, -1
	s_mov_b32 m0, s77
	s_nop 0
	global_load_lds_dwordx4 v212, s[52:53]
	s_add_u32 s52, s54, 0xffffe000
	s_addc_u32 s53, s55, -1
	s_mov_b32 m0, s81
	s_nop 0
	global_load_lds_dwordx4 v212, s[52:53]
	s_waitcnt vmcnt(8)
	s_waitcnt lgkmcnt(0)
	s_add_u32 s52, s60, 0x8000
	s_addc_u32 s53, s61, 0
	s_barrier
	s_setprio 1
	s_waitcnt lgkmcnt(7)
	v_mfma_f32_16x16x32_bf16 v[164:167], v[48:51], v[156:159], v[164:167]
	v_mfma_f32_16x16x32_bf16 v[160:163], v[80:83], v[156:159], v[160:163]
	s_waitcnt lgkmcnt(5)
	v_mfma_f32_16x16x32_bf16 v[136:139], v[48:51], v[172:175], v[136:139]
	v_mfma_f32_16x16x32_bf16 v[130:133], v[80:83], v[172:175], v[132:135]
	s_waitcnt lgkmcnt(3)
	v_mfma_f32_16x16x32_bf16 v[112:115], v[48:51], v[180:183], v[112:115]
	v_mfma_f32_16x16x32_bf16 v[108:111], v[80:83], v[180:183], v[108:111]
	s_waitcnt lgkmcnt(1)
	v_mfma_f32_16x16x32_bf16 v[88:91], v[48:51], v[188:191], v[88:91]
	v_mfma_f32_16x16x32_bf16 v[84:87], v[80:83], v[188:191], v[84:87]
	v_mfma_f32_16x16x32_bf16 v[164:167], v[64:67], v[168:171], v[164:167]
	v_mfma_f32_16x16x32_bf16 v[160:163], v[92:95], v[168:171], v[160:163]
	v_mfma_f32_16x16x32_bf16 v[136:139], v[64:67], v[176:179], v[136:139]
	v_mfma_f32_16x16x32_bf16 v[130:133], v[92:95], v[176:179], v[130:133]
	v_mfma_f32_16x16x32_bf16 v[112:115], v[64:67], v[184:187], v[112:115]
	v_mfma_f32_16x16x32_bf16 v[108:111], v[92:95], v[184:187], v[108:111]
	s_waitcnt lgkmcnt(0)
	v_mfma_f32_16x16x32_bf16 v[88:91], v[64:67], v[194:197], v[88:91]
	v_mfma_f32_16x16x32_bf16 v[84:87], v[92:95], v[194:197], v[84:87]
	s_setprio 0
	s_setprio 1
	s_waitcnt lgkmcnt(0)
	v_mfma_f32_16x16x32_bf16 v[152:155], v[104:107], v[156:159], v[152:155]
	v_mfma_f32_16x16x32_bf16 v[152:155], v[116:119], v[168:171], v[152:155]
	v_mfma_f32_16x16x32_bf16 v[148:151], v[140:143], v[156:159], v[148:151]
	v_mfma_f32_16x16x32_bf16 v[148:151], v[144:147], v[168:171], v[148:151]
	v_mfma_f32_16x16x32_bf16 v[120:123], v[140:143], v[172:175], v[120:123]
	v_mfma_f32_16x16x32_bf16 v[120:123], v[144:147], v[176:179], v[120:123]
	v_mfma_f32_16x16x32_bf16 v[124:127], v[104:107], v[172:175], v[124:127]
	v_mfma_f32_16x16x32_bf16 v[124:127], v[116:119], v[176:179], v[124:127]
	v_mfma_f32_16x16x32_bf16 v[100:103], v[104:107], v[180:183], v[100:103]
	v_mfma_f32_16x16x32_bf16 v[100:103], v[116:119], v[184:187], v[100:103]
	v_mfma_f32_16x16x32_bf16 v[96:99], v[140:143], v[180:183], v[96:99]
	v_mfma_f32_16x16x32_bf16 v[96:99], v[144:147], v[184:187], v[96:99]
	v_mfma_f32_16x16x32_bf16 v[72:75], v[140:143], v[188:191], v[72:75]
	v_mfma_f32_16x16x32_bf16 v[72:75], v[144:147], v[194:197], v[72:75]
	v_mfma_f32_16x16x32_bf16 v[76:79], v[104:107], v[188:191], v[76:79]
	v_mfma_f32_16x16x32_bf16 v[76:79], v[116:119], v[194:197], v[76:79]
	s_setprio 0
	s_barrier
	s_add_u32 s96, s60, 0x2000
	ds_read_b128 v[156:159], v216 offset:16384
	ds_read_b128 v[168:171], v216 offset:17408
	ds_read_b128 v[172:175], v216 offset:18432
	ds_read_b128 v[176:179], v216 offset:19456
	ds_read_b128 v[180:183], v216 offset:20480
	ds_read_b128 v[184:187], v216 offset:21504
	ds_read_b128 v[188:191], v216 offset:22528
	ds_read_b128 v[194:197], v216 offset:23552
	s_mov_b32 m0, s49
	s_nop 0
	global_load_lds_dwordx4 v212, s[60:61]
	s_addc_u32 s97, s61, 0
	s_mov_b32 m0, s57
	s_nop 0
	global_load_lds_dwordx4 v212, s[96:97]
	s_add_u32 s96, s60, 0x4000
	s_addc_u32 s97, s61, 0
	s_mov_b32 m0, s63
	s_nop 0
	global_load_lds_dwordx4 v212, s[96:97]
	s_add_u32 s96, s60, 0x6000
	s_addc_u32 s97, s61, 0
	s_mov_b32 m0, s64
	s_nop 0
	global_load_lds_dwordx4 v212, s[96:97]
	s_add_u32 s96, s2, 0x2000
	s_mov_b32 m0, s62
	s_nop 0
	global_load_lds_dwordx4 v212, s[2:3]
	s_addc_u32 s97, s3, 0
	s_mov_b32 m0, s65
	s_nop 0
	global_load_lds_dwordx4 v212, s[96:97]
	s_waitcnt vmcnt(8)
	s_waitcnt lgkmcnt(0)
	s_barrier
	s_setprio 1
	s_waitcnt lgkmcnt(7)
	s_waitcnt lgkmcnt(0)
	v_mfma_f32_16x16x32_bf16 v[68:71], v[48:51], v[156:159], v[68:71]
	v_mfma_f32_16x16x32_bf16 v[68:71], v[64:67], v[168:171], v[68:71]
	v_mfma_f32_16x16x32_bf16 v[60:63], v[80:83], v[156:159], v[60:63]
	v_mfma_f32_16x16x32_bf16 v[60:63], v[92:95], v[168:171], v[60:63]
	v_mfma_f32_16x16x32_bf16 v[40:43], v[80:83], v[172:175], v[40:43]
	v_mfma_f32_16x16x32_bf16 v[40:43], v[92:95], v[176:179], v[40:43]
	v_mfma_f32_16x16x32_bf16 v[44:47], v[48:51], v[172:175], v[44:47]
	v_mfma_f32_16x16x32_bf16 v[44:47], v[64:67], v[176:179], v[44:47]
	v_mfma_f32_16x16x32_bf16 v[28:31], v[48:51], v[180:183], v[28:31]
	v_mfma_f32_16x16x32_bf16 v[28:31], v[64:67], v[184:187], v[28:31]
	v_mfma_f32_16x16x32_bf16 v[24:27], v[80:83], v[180:183], v[24:27]
	v_mfma_f32_16x16x32_bf16 v[24:27], v[92:95], v[184:187], v[24:27]
	v_mfma_f32_16x16x32_bf16 v[8:11], v[80:83], v[188:191], v[8:11]
	v_mfma_f32_16x16x32_bf16 v[8:11], v[92:95], v[194:197], v[8:11]
	v_mfma_f32_16x16x32_bf16 v[12:15], v[48:51], v[188:191], v[12:15]
	v_mfma_f32_16x16x32_bf16 v[12:15], v[64:67], v[194:197], v[12:15]
	s_setprio 0
	s_setprio 1
	v_mfma_f32_16x16x32_bf16 v[52:55], v[140:143], v[156:159], v[52:55]
	v_mfma_f32_16x16x32_bf16 v[36:39], v[104:107], v[172:175], v[36:39]
	v_mfma_f32_16x16x32_bf16 v[32:35], v[140:143], v[172:175], v[32:35]
	v_mfma_f32_16x16x32_bf16 v[20:23], v[104:107], v[180:183], v[20:23]
	v_mfma_f32_16x16x32_bf16 v[16:19], v[140:143], v[180:183], v[16:19]
	v_mfma_f32_16x16x32_bf16 v[4:7], v[104:107], v[188:191], v[4:7]
	v_mfma_f32_16x16x32_bf16 v[0:3], v[140:143], v[188:191], v[0:3]
	v_mfma_f32_16x16x32_bf16 v[48:51], v[104:107], v[156:159], v[56:59]
	v_mfma_f32_16x16x32_bf16 v[52:55], v[144:147], v[168:171], v[52:55]
	v_mfma_f32_16x16x32_bf16 v[36:39], v[116:119], v[176:179], v[36:39]
	v_mfma_f32_16x16x32_bf16 v[32:35], v[144:147], v[176:179], v[32:35]
	v_mfma_f32_16x16x32_bf16 v[20:23], v[116:119], v[184:187], v[20:23]
	v_mfma_f32_16x16x32_bf16 v[16:19], v[144:147], v[184:187], v[16:19]
	v_mfma_f32_16x16x32_bf16 v[4:7], v[116:119], v[194:197], v[4:7]
	v_mfma_f32_16x16x32_bf16 v[0:3], v[144:147], v[194:197], v[0:3]
	v_mfma_f32_16x16x32_bf16 v[48:51], v[116:119], v[168:171], v[48:51]
	s_setprio 0
	s_barrier
	ds_read_b128 v[56:59], v128
	ds_read_b128 v[64:67], v128 offset:1024
	ds_read_b128 v[80:83], v128 offset:2048
	ds_read_b128 v[92:95], v128 offset:3072
	ds_read_b128 v[104:107], v129
	ds_read_b128 v[116:119], v129 offset:1024
	ds_read_b128 v[140:143], v129 offset:2048
	ds_read_b128 v[144:147], v129 offset:3072
	ds_read_b128 v[156:159], v216 offset:32768
	ds_read_b128 v[168:171], v216 offset:33792
	ds_read_b128 v[172:175], v216 offset:34816
	ds_read_b128 v[176:179], v216 offset:35840
	ds_read_b128 v[180:183], v216 offset:36864
	ds_read_b128 v[184:187], v216 offset:37888
	ds_read_b128 v[188:191], v216 offset:38912
	ds_read_b128 v[194:197], v216 offset:39936
	s_add_u32 s96, s2, 0x4000
	s_addc_u32 s97, s3, 0
	s_mov_b32 m0, s66
	s_nop 0
	global_load_lds_dwordx4 v212, s[96:97]
	s_add_u32 s96, s2, 0x6000
	s_addc_u32 s97, s3, 0
	s_mov_b32 m0, s67
	s_nop 0
	global_load_lds_dwordx4 v212, s[96:97]
	s_waitcnt vmcnt(8)
	s_waitcnt lgkmcnt(0)
	s_barrier
	s_setprio 1
	s_waitcnt lgkmcnt(7)
	v_mfma_f32_16x16x32_bf16 v[164:167], v[56:59], v[156:159], v[164:167]
	v_mfma_f32_16x16x32_bf16 v[160:163], v[80:83], v[156:159], v[160:163]
	s_waitcnt lgkmcnt(5)
	v_mfma_f32_16x16x32_bf16 v[134:137], v[56:59], v[172:175], v[136:139]
	v_mfma_f32_16x16x32_bf16 v[130:133], v[80:83], v[172:175], v[130:133]
	s_waitcnt lgkmcnt(3)
	v_mfma_f32_16x16x32_bf16 v[112:115], v[56:59], v[180:183], v[112:115]
	v_mfma_f32_16x16x32_bf16 v[108:111], v[80:83], v[180:183], v[108:111]
	s_waitcnt lgkmcnt(1)
	v_mfma_f32_16x16x32_bf16 v[88:91], v[56:59], v[188:191], v[88:91]
	v_mfma_f32_16x16x32_bf16 v[84:87], v[80:83], v[188:191], v[84:87]
	v_mfma_f32_16x16x32_bf16 v[164:167], v[64:67], v[168:171], v[164:167]
	v_mfma_f32_16x16x32_bf16 v[160:163], v[92:95], v[168:171], v[160:163]
	v_mfma_f32_16x16x32_bf16 v[136:139], v[64:67], v[176:179], v[134:137]
	v_mfma_f32_16x16x32_bf16 v[132:135], v[92:95], v[176:179], v[130:133]
	v_mfma_f32_16x16x32_bf16 v[112:115], v[64:67], v[184:187], v[112:115]
	v_mfma_f32_16x16x32_bf16 v[108:111], v[92:95], v[184:187], v[108:111]
	s_waitcnt lgkmcnt(0)
	v_mfma_f32_16x16x32_bf16 v[88:91], v[64:67], v[194:197], v[88:91]
	v_mfma_f32_16x16x32_bf16 v[84:87], v[92:95], v[194:197], v[84:87]
	s_setprio 0
	s_setprio 1
	s_waitcnt lgkmcnt(0)
	v_mfma_f32_16x16x32_bf16 v[152:155], v[104:107], v[156:159], v[152:155]
	v_mfma_f32_16x16x32_bf16 v[152:155], v[116:119], v[168:171], v[152:155]
	v_mfma_f32_16x16x32_bf16 v[148:151], v[140:143], v[156:159], v[148:151]
	v_mfma_f32_16x16x32_bf16 v[148:151], v[144:147], v[168:171], v[148:151]
	v_mfma_f32_16x16x32_bf16 v[120:123], v[140:143], v[172:175], v[120:123]
	v_mfma_f32_16x16x32_bf16 v[120:123], v[144:147], v[176:179], v[120:123]
	v_mfma_f32_16x16x32_bf16 v[124:127], v[104:107], v[172:175], v[124:127]
	v_mfma_f32_16x16x32_bf16 v[124:127], v[116:119], v[176:179], v[124:127]
	v_mfma_f32_16x16x32_bf16 v[100:103], v[104:107], v[180:183], v[100:103]
	v_mfma_f32_16x16x32_bf16 v[100:103], v[116:119], v[184:187], v[100:103]
	v_mfma_f32_16x16x32_bf16 v[96:99], v[140:143], v[180:183], v[96:99]
	v_mfma_f32_16x16x32_bf16 v[96:99], v[144:147], v[184:187], v[96:99]
	v_mfma_f32_16x16x32_bf16 v[72:75], v[140:143], v[188:191], v[72:75]
	v_mfma_f32_16x16x32_bf16 v[72:75], v[144:147], v[194:197], v[72:75]
	v_mfma_f32_16x16x32_bf16 v[76:79], v[104:107], v[188:191], v[76:79]
	v_mfma_f32_16x16x32_bf16 v[76:79], v[116:119], v[194:197], v[76:79]
	s_setprio 0
	s_barrier
	ds_read_b128 v[156:159], v216 offset:49152
	ds_read_b128 v[168:171], v216 offset:50176
	ds_read_b128 v[172:175], v216 offset:51200
	ds_read_b128 v[176:179], v216 offset:52224
	ds_read_b128 v[180:183], v216 offset:53248
	ds_read_b128 v[184:187], v216 offset:54272
	ds_read_b128 v[188:191], v216 offset:55296
	ds_read_b128 v[194:197], v216 offset:56320
	s_mov_b32 m0, s71
	s_nop 0
	global_load_lds_dwordx4 v212, s[52:53]
	s_add_u32 s52, s60, 0xa000
	s_addc_u32 s53, s61, 0
	s_mov_b32 m0, s72
	s_nop 0
	global_load_lds_dwordx4 v212, s[52:53]
	s_add_u32 s52, s60, 0xc000
	s_addc_u32 s53, s61, 0
	s_mov_b32 m0, s75
	s_nop 0
	global_load_lds_dwordx4 v212, s[52:53]
	s_add_u32 s52, s60, 0xe000
	s_addc_u32 s53, s61, 0
	s_mov_b32 m0, s76
	s_nop 0
	global_load_lds_dwordx4 v212, s[52:53]
	s_add_u32 s2, s2, 0xa000
	s_mov_b32 m0, s73
	s_nop 0
	global_load_lds_dwordx4 v212, s[58:59]
	s_addc_u32 s3, s3, 0
	s_mov_b32 m0, s74
	s_nop 0
	global_load_lds_dwordx4 v212, s[2:3]
	s_waitcnt vmcnt(8)
	s_waitcnt lgkmcnt(0)
	s_barrier
	s_setprio 1
	s_waitcnt lgkmcnt(7)
	s_waitcnt lgkmcnt(0)
	v_mfma_f32_16x16x32_bf16 v[68:71], v[56:59], v[156:159], v[68:71]
	v_mfma_f32_16x16x32_bf16 v[68:71], v[64:67], v[168:171], v[68:71]
	v_mfma_f32_16x16x32_bf16 v[60:63], v[80:83], v[156:159], v[60:63]
	v_mfma_f32_16x16x32_bf16 v[60:63], v[92:95], v[168:171], v[60:63]
	v_mfma_f32_16x16x32_bf16 v[40:43], v[80:83], v[172:175], v[40:43]
	v_mfma_f32_16x16x32_bf16 v[40:43], v[92:95], v[176:179], v[40:43]
	v_mfma_f32_16x16x32_bf16 v[44:47], v[56:59], v[172:175], v[44:47]
	v_mfma_f32_16x16x32_bf16 v[44:47], v[64:67], v[176:179], v[44:47]
	v_mfma_f32_16x16x32_bf16 v[28:31], v[56:59], v[180:183], v[28:31]
	v_mfma_f32_16x16x32_bf16 v[28:31], v[64:67], v[184:187], v[28:31]
	v_mfma_f32_16x16x32_bf16 v[24:27], v[80:83], v[180:183], v[24:27]
	v_mfma_f32_16x16x32_bf16 v[24:27], v[92:95], v[184:187], v[24:27]
	v_mfma_f32_16x16x32_bf16 v[8:11], v[80:83], v[188:191], v[8:11]
	v_mfma_f32_16x16x32_bf16 v[8:11], v[92:95], v[194:197], v[8:11]
	v_mfma_f32_16x16x32_bf16 v[12:15], v[56:59], v[188:191], v[12:15]
	v_mfma_f32_16x16x32_bf16 v[12:15], v[64:67], v[194:197], v[12:15]
	s_setprio 0
	s_setprio 1
	v_mfma_f32_16x16x32_bf16 v[48:51], v[104:107], v[156:159], v[48:51]
	v_mfma_f32_16x16x32_bf16 v[56:59], v[116:119], v[168:171], v[48:51]
	v_mfma_f32_16x16x32_bf16 v[48:51], v[140:143], v[156:159], v[52:55]
	v_mfma_f32_16x16x32_bf16 v[36:39], v[104:107], v[172:175], v[36:39]
	v_mfma_f32_16x16x32_bf16 v[32:35], v[140:143], v[172:175], v[32:35]
	v_mfma_f32_16x16x32_bf16 v[20:23], v[104:107], v[180:183], v[20:23]
	v_mfma_f32_16x16x32_bf16 v[16:19], v[140:143], v[180:183], v[16:19]
	v_mfma_f32_16x16x32_bf16 v[4:7], v[104:107], v[188:191], v[4:7]
	v_mfma_f32_16x16x32_bf16 v[0:3], v[140:143], v[188:191], v[0:3]
	v_mfma_f32_16x16x32_bf16 v[52:55], v[144:147], v[168:171], v[48:51]
	v_mfma_f32_16x16x32_bf16 v[36:39], v[116:119], v[176:179], v[36:39]
	v_mfma_f32_16x16x32_bf16 v[32:35], v[144:147], v[176:179], v[32:35]
	v_mfma_f32_16x16x32_bf16 v[20:23], v[116:119], v[184:187], v[20:23]
	v_mfma_f32_16x16x32_bf16 v[16:19], v[144:147], v[184:187], v[16:19]
	v_mfma_f32_16x16x32_bf16 v[4:7], v[116:119], v[194:197], v[4:7]
	v_mfma_f32_16x16x32_bf16 v[0:3], v[144:147], v[194:197], v[0:3]
	s_setprio 0
	s_barrier
	s_add_i32 s93, s93, 2
	s_add_u32 s54, s54, 0x10000
	s_addc_u32 s55, s55, 0
	s_add_u32 s91, s91, 0x10000
	s_addc_u32 s92, s92, 0
	s_cmp_gt_u32 s93, 5
	s_cbranch_scc0 .LBB0_1675
	s_and_b64 vcc, exec, s[14:15]
	s_cbranch_vccz .LBB0_1678
	s_barrier

.LBB0_1953:
	ds_read_b128 v[134:137], v128
	ds_read_b128 v[138:141], v128 offset:1024
	ds_read_b128 v[142:145], v128 offset:2048
	ds_read_b128 v[146:149], v128 offset:3072
	ds_read_b128 v[150:153], v129
	ds_read_b128 v[154:157], v129 offset:1024
	ds_read_b128 v[158:161], v129 offset:2048
	ds_read_b128 v[162:165], v129 offset:3072
	s_add_u32 s2, s28, 0x10000
	s_addc_u32 s3, s29, 0
	s_cmp_eq_u32 s77, 8
	s_cselect_b32 s38, s26, s2
	s_cselect_b32 s39, s27, s3
	s_cselect_b32 s42, s23, s75
	s_cselect_b32 s43, s25, s76
	s_add_u32 s40, s38, 0x8000
	s_addc_u32 s41, s39, 0
	ds_read_b128 v[166:169], v130
	ds_read_b128 v[170:173], v130 offset:1024
	ds_read_b128 v[174:177], v130 offset:2048
	ds_read_b128 v[178:181], v130 offset:3072
	ds_read_b128 v[182:185], v130 offset:4096
	ds_read_b128 v[192:195], v130 offset:5120
	ds_read_b128 v[196:199], v130 offset:6144
	ds_read_b128 v[200:203], v130 offset:7168
	s_add_u32 s78, s28, 0xc000
	s_addc_u32 s79, s29, 0
	s_mov_b32 m0, s63
	s_nop 0
	global_load_lds_dwordx4 v210, s[78:79]
	s_add_u32 s28, s28, 0xe000
	s_addc_u32 s29, s29, 0
	s_mov_b32 m0, s66
	s_nop 0
	global_load_lds_dwordx4 v210, s[28:29]
	s_waitcnt vmcnt(8)
	s_waitcnt lgkmcnt(0)
	s_barrier
	s_setprio 1
	s_waitcnt lgkmcnt(7)
	s_waitcnt lgkmcnt(0)
	v_mfma_f32_16x16x32_bf16 v[124:127], v[134:137], v[166:169], v[124:127]
	v_mfma_f32_16x16x32_bf16 v[124:127], v[138:141], v[170:173], v[124:127]
	v_mfma_f32_16x16x32_bf16 v[120:123], v[142:145], v[166:169], v[120:123]
	v_mfma_f32_16x16x32_bf16 v[120:123], v[146:149], v[170:173], v[120:123]
	v_mfma_f32_16x16x32_bf16 v[104:107], v[142:145], v[174:177], v[104:107]
	v_mfma_f32_16x16x32_bf16 v[104:107], v[146:149], v[178:181], v[104:107]
	v_mfma_f32_16x16x32_bf16 v[108:111], v[134:137], v[174:177], v[108:111]
	v_mfma_f32_16x16x32_bf16 v[108:111], v[138:141], v[178:181], v[108:111]
	v_mfma_f32_16x16x32_bf16 v[92:95], v[134:137], v[182:185], v[92:95]
	v_mfma_f32_16x16x32_bf16 v[92:95], v[138:141], v[192:195], v[92:95]
	v_mfma_f32_16x16x32_bf16 v[88:91], v[142:145], v[182:185], v[88:91]
	v_mfma_f32_16x16x32_bf16 v[88:91], v[146:149], v[192:195], v[88:91]
	v_mfma_f32_16x16x32_bf16 v[72:75], v[142:145], v[196:199], v[72:75]
	v_mfma_f32_16x16x32_bf16 v[72:75], v[146:149], v[200:203], v[72:75]
	v_mfma_f32_16x16x32_bf16 v[76:79], v[134:137], v[196:199], v[76:79]
	v_mfma_f32_16x16x32_bf16 v[76:79], v[138:141], v[200:203], v[76:79]
	s_setprio 0
	s_setprio 1
	s_waitcnt lgkmcnt(0)
	v_mfma_f32_16x16x32_bf16 v[116:119], v[150:153], v[166:169], v[116:119]
	v_mfma_f32_16x16x32_bf16 v[116:119], v[154:157], v[170:173], v[116:119]
	v_mfma_f32_16x16x32_bf16 v[112:115], v[158:161], v[166:169], v[112:115]
	v_mfma_f32_16x16x32_bf16 v[112:115], v[162:165], v[170:173], v[112:115]
	v_mfma_f32_16x16x32_bf16 v[96:99], v[158:161], v[174:177], v[96:99]
	v_mfma_f32_16x16x32_bf16 v[96:99], v[162:165], v[178:181], v[96:99]
	v_mfma_f32_16x16x32_bf16 v[100:103], v[150:153], v[174:177], v[100:103]
	v_mfma_f32_16x16x32_bf16 v[100:103], v[154:157], v[178:181], v[100:103]
	v_mfma_f32_16x16x32_bf16 v[84:87], v[150:153], v[182:185], v[84:87]
	v_mfma_f32_16x16x32_bf16 v[84:87], v[154:157], v[192:195], v[84:87]
	v_mfma_f32_16x16x32_bf16 v[80:83], v[158:161], v[182:185], v[80:83]
	v_mfma_f32_16x16x32_bf16 v[80:83], v[162:165], v[192:195], v[80:83]
	v_mfma_f32_16x16x32_bf16 v[64:67], v[158:161], v[196:199], v[64:67]
	v_mfma_f32_16x16x32_bf16 v[64:67], v[162:165], v[200:203], v[64:67]
	v_mfma_f32_16x16x32_bf16 v[68:71], v[150:153], v[196:199], v[68:71]
	v_mfma_f32_16x16x32_bf16 v[68:71], v[154:157], v[200:203], v[68:71]
	s_setprio 0
	s_barrier
	s_add_u32 s28, s42, 0x2000
	ds_read_b128 v[166:169], v130 offset:16384
	ds_read_b128 v[170:173], v130 offset:17408
	ds_read_b128 v[174:177], v130 offset:18432
	ds_read_b128 v[178:181], v130 offset:19456
	ds_read_b128 v[182:185], v130 offset:20480
	ds_read_b128 v[192:195], v130 offset:21504
	ds_read_b128 v[196:199], v130 offset:22528
	ds_read_b128 v[200:203], v130 offset:23552
	s_mov_b32 m0, s46
	s_nop 0
	global_load_lds_dwordx4 v210, s[42:43]
	s_addc_u32 s29, s43, 0
	s_mov_b32 m0, s47
	s_nop 0
	global_load_lds_dwordx4 v210, s[28:29]
	s_add_u32 s28, s42, 0x4000
	s_addc_u32 s29, s43, 0
	s_mov_b32 m0, s48
	s_nop 0
	global_load_lds_dwordx4 v210, s[28:29]
	s_add_u32 s28, s42, 0x6000
	s_addc_u32 s29, s43, 0
	s_mov_b32 m0, s49
	s_nop 0
	global_load_lds_dwordx4 v210, s[28:29]
	s_add_u32 s28, s38, 0x2000
	s_mov_b32 m0, s45
	s_nop 0
	global_load_lds_dwordx4 v210, s[38:39]
	s_addc_u32 s29, s39, 0
	s_mov_b32 m0, s50
	s_nop 0
	global_load_lds_dwordx4 v210, s[28:29]
	s_waitcnt vmcnt(8)
	s_waitcnt lgkmcnt(0)
	s_barrier
	s_setprio 1
	s_waitcnt lgkmcnt(7)
	s_waitcnt lgkmcnt(0)
	v_mfma_f32_16x16x32_bf16 v[60:63], v[134:137], v[166:169], v[60:63]
	v_mfma_f32_16x16x32_bf16 v[60:63], v[138:141], v[170:173], v[60:63]
	v_mfma_f32_16x16x32_bf16 v[56:59], v[142:145], v[166:169], v[56:59]
	v_mfma_f32_16x16x32_bf16 v[56:59], v[146:149], v[170:173], v[56:59]
	v_mfma_f32_16x16x32_bf16 v[40:43], v[142:145], v[174:177], v[40:43]
	v_mfma_f32_16x16x32_bf16 v[40:43], v[146:149], v[178:181], v[40:43]
	v_mfma_f32_16x16x32_bf16 v[44:47], v[134:137], v[174:177], v[44:47]
	v_mfma_f32_16x16x32_bf16 v[44:47], v[138:141], v[178:181], v[44:47]
	v_mfma_f32_16x16x32_bf16 v[28:31], v[134:137], v[182:185], v[28:31]
	v_mfma_f32_16x16x32_bf16 v[28:31], v[138:141], v[192:195], v[28:31]
	v_mfma_f32_16x16x32_bf16 v[24:27], v[142:145], v[182:185], v[24:27]
	v_mfma_f32_16x16x32_bf16 v[24:27], v[146:149], v[192:195], v[24:27]
	v_mfma_f32_16x16x32_bf16 v[8:11], v[142:145], v[196:199], v[8:11]
	v_mfma_f32_16x16x32_bf16 v[8:11], v[146:149], v[200:203], v[8:11]
	v_mfma_f32_16x16x32_bf16 v[12:15], v[134:137], v[196:199], v[12:15]
	v_mfma_f32_16x16x32_bf16 v[12:15], v[138:141], v[200:203], v[12:15]
	s_setprio 0
	s_setprio 1
	s_waitcnt lgkmcnt(0)
	v_mfma_f32_16x16x32_bf16 v[52:55], v[150:153], v[166:169], v[52:55]
	v_mfma_f32_16x16x32_bf16 v[52:55], v[154:157], v[170:173], v[52:55]
	v_mfma_f32_16x16x32_bf16 v[48:51], v[158:161], v[166:169], v[48:51]
	v_mfma_f32_16x16x32_bf16 v[48:51], v[162:165], v[170:173], v[48:51]
	v_mfma_f32_16x16x32_bf16 v[32:35], v[158:161], v[174:177], v[32:35]
	v_mfma_f32_16x16x32_bf16 v[32:35], v[162:165], v[178:181], v[32:35]
	v_mfma_f32_16x16x32_bf16 v[36:39], v[150:153], v[174:177], v[36:39]
	v_mfma_f32_16x16x32_bf16 v[36:39], v[154:157], v[178:181], v[36:39]
	v_mfma_f32_16x16x32_bf16 v[20:23], v[150:153], v[182:185], v[20:23]
	v_mfma_f32_16x16x32_bf16 v[20:23], v[154:157], v[192:195], v[20:23]
	v_mfma_f32_16x16x32_bf16 v[16:19], v[158:161], v[182:185], v[16:19]
	v_mfma_f32_16x16x32_bf16 v[16:19], v[162:165], v[192:195], v[16:19]
	v_mfma_f32_16x16x32_bf16 v[0:3], v[158:161], v[196:199], v[0:3]
	v_mfma_f32_16x16x32_bf16 v[0:3], v[162:165], v[200:203], v[0:3]
	v_mfma_f32_16x16x32_bf16 v[4:7], v[150:153], v[196:199], v[4:7]
	v_mfma_f32_16x16x32_bf16 v[4:7], v[154:157], v[200:203], v[4:7]
	s_setprio 0
	s_barrier
	ds_read_b128 v[134:137], v131
	ds_read_b128 v[138:141], v131 offset:1024
	ds_read_b128 v[142:145], v131 offset:2048
	ds_read_b128 v[146:149], v131 offset:3072
	ds_read_b128 v[150:153], v132
	ds_read_b128 v[154:157], v132 offset:1024
	ds_read_b128 v[158:161], v132 offset:2048
	ds_read_b128 v[162:165], v132 offset:3072
	ds_read_b128 v[166:169], v130 offset:32768
	ds_read_b128 v[170:173], v130 offset:33792
	ds_read_b128 v[174:177], v130 offset:34816
	ds_read_b128 v[178:181], v130 offset:35840
	ds_read_b128 v[182:185], v130 offset:36864
	ds_read_b128 v[192:195], v130 offset:37888
	ds_read_b128 v[196:199], v130 offset:38912
	ds_read_b128 v[200:203], v130 offset:39936
	s_add_u32 s28, s38, 0x4000
	s_addc_u32 s29, s39, 0
	s_mov_b32 m0, s51
	s_nop 0
	global_load_lds_dwordx4 v210, s[28:29]
	s_add_u32 s28, s38, 0x6000
	s_addc_u32 s29, s39, 0
	s_mov_b32 m0, s52
	s_nop 0
	global_load_lds_dwordx4 v210, s[28:29]
	s_waitcnt vmcnt(8)
	s_waitcnt lgkmcnt(0)
	s_barrier
	s_setprio 1
	s_waitcnt lgkmcnt(7)
	s_waitcnt lgkmcnt(0)
	v_mfma_f32_16x16x32_bf16 v[124:127], v[134:137], v[166:169], v[124:127]
	v_mfma_f32_16x16x32_bf16 v[124:127], v[138:141], v[170:173], v[124:127]
	v_mfma_f32_16x16x32_bf16 v[120:123], v[142:145], v[166:169], v[120:123]
	v_mfma_f32_16x16x32_bf16 v[120:123], v[146:149], v[170:173], v[120:123]
	v_mfma_f32_16x16x32_bf16 v[104:107], v[142:145], v[174:177], v[104:107]
	v_mfma_f32_16x16x32_bf16 v[104:107], v[146:149], v[178:181], v[104:107]
	v_mfma_f32_16x16x32_bf16 v[108:111], v[134:137], v[174:177], v[108:111]
	v_mfma_f32_16x16x32_bf16 v[108:111], v[138:141], v[178:181], v[108:111]
	v_mfma_f32_16x16x32_bf16 v[92:95], v[134:137], v[182:185], v[92:95]
	v_mfma_f32_16x16x32_bf16 v[92:95], v[138:141], v[192:195], v[92:95]
	v_mfma_f32_16x16x32_bf16 v[88:91], v[142:145], v[182:185], v[88:91]
	v_mfma_f32_16x16x32_bf16 v[88:91], v[146:149], v[192:195], v[88:91]
	v_mfma_f32_16x16x32_bf16 v[72:75], v[142:145], v[196:199], v[72:75]
	v_mfma_f32_16x16x32_bf16 v[72:75], v[146:149], v[200:203], v[72:75]
	v_mfma_f32_16x16x32_bf16 v[76:79], v[134:137], v[196:199], v[76:79]
	v_mfma_f32_16x16x32_bf16 v[76:79], v[138:141], v[200:203], v[76:79]
	s_setprio 0
	s_setprio 1
	s_waitcnt lgkmcnt(0)
	v_mfma_f32_16x16x32_bf16 v[116:119], v[150:153], v[166:169], v[116:119]
	v_mfma_f32_16x16x32_bf16 v[116:119], v[154:157], v[170:173], v[116:119]
	v_mfma_f32_16x16x32_bf16 v[112:115], v[158:161], v[166:169], v[112:115]
	v_mfma_f32_16x16x32_bf16 v[112:115], v[162:165], v[170:173], v[112:115]
	v_mfma_f32_16x16x32_bf16 v[96:99], v[158:161], v[174:177], v[96:99]
	v_mfma_f32_16x16x32_bf16 v[96:99], v[162:165], v[178:181], v[96:99]
	v_mfma_f32_16x16x32_bf16 v[100:103], v[150:153], v[174:177], v[100:103]
	v_mfma_f32_16x16x32_bf16 v[100:103], v[154:157], v[178:181], v[100:103]
	v_mfma_f32_16x16x32_bf16 v[84:87], v[150:153], v[182:185], v[84:87]
	v_mfma_f32_16x16x32_bf16 v[84:87], v[154:157], v[192:195], v[84:87]
	v_mfma_f32_16x16x32_bf16 v[80:83], v[158:161], v[182:185], v[80:83]
	v_mfma_f32_16x16x32_bf16 v[80:83], v[162:165], v[192:195], v[80:83]
	v_mfma_f32_16x16x32_bf16 v[64:67], v[158:161], v[196:199], v[64:67]
	v_mfma_f32_16x16x32_bf16 v[64:67], v[162:165], v[200:203], v[64:67]
	v_mfma_f32_16x16x32_bf16 v[68:71], v[150:153], v[196:199], v[68:71]
	v_mfma_f32_16x16x32_bf16 v[68:71], v[154:157], v[200:203], v[68:71]
	s_setprio 0
	s_barrier
	s_add_u32 s28, s42, 0x8000
	s_addc_u32 s29, s43, 0
	ds_read_b128 v[166:169], v130 offset:49152
	ds_read_b128 v[170:173], v130 offset:50176
	ds_read_b128 v[174:177], v130 offset:51200
	ds_read_b128 v[178:181], v130 offset:52224
	ds_read_b128 v[182:185], v130 offset:53248
	ds_read_b128 v[192:195], v130 offset:54272
	ds_read_b128 v[196:199], v130 offset:55296
	ds_read_b128 v[200:203], v130 offset:56320
	s_mov_b32 m0, s53
	s_nop 0
	global_load_lds_dwordx4 v210, s[28:29]
	s_add_u32 s28, s42, 0xa000
	s_addc_u32 s29, s43, 0
	s_mov_b32 m0, s54
	s_nop 0
	global_load_lds_dwordx4 v210, s[28:29]
	s_add_u32 s28, s42, 0xc000
	s_addc_u32 s29, s43, 0
	s_mov_b32 m0, s57
	s_nop 0
	global_load_lds_dwordx4 v210, s[28:29]
	s_add_u32 s28, s42, 0xe000
	s_addc_u32 s29, s43, 0
	s_mov_b32 m0, s58
	s_nop 0
	global_load_lds_dwordx4 v210, s[28:29]
	s_add_u32 s28, s38, 0xa000
	s_mov_b32 m0, s55
	s_nop 0
	global_load_lds_dwordx4 v210, s[40:41]
	s_addc_u32 s29, s39, 0
	s_mov_b32 m0, s56
	s_nop 0
	global_load_lds_dwordx4 v210, s[28:29]
	s_waitcnt vmcnt(8)
	s_waitcnt lgkmcnt(0)
	s_barrier
	s_setprio 1
	s_waitcnt lgkmcnt(7)
	s_waitcnt lgkmcnt(0)
	v_mfma_f32_16x16x32_bf16 v[60:63], v[134:137], v[166:169], v[60:63]
	v_mfma_f32_16x16x32_bf16 v[60:63], v[138:141], v[170:173], v[60:63]
	v_mfma_f32_16x16x32_bf16 v[56:59], v[142:145], v[166:169], v[56:59]
	v_mfma_f32_16x16x32_bf16 v[56:59], v[146:149], v[170:173], v[56:59]
	v_mfma_f32_16x16x32_bf16 v[40:43], v[142:145], v[174:177], v[40:43]
	v_mfma_f32_16x16x32_bf16 v[40:43], v[146:149], v[178:181], v[40:43]
	v_mfma_f32_16x16x32_bf16 v[44:47], v[134:137], v[174:177], v[44:47]
	v_mfma_f32_16x16x32_bf16 v[44:47], v[138:141], v[178:181], v[44:47]
	v_mfma_f32_16x16x32_bf16 v[28:31], v[134:137], v[182:185], v[28:31]
	v_mfma_f32_16x16x32_bf16 v[28:31], v[138:141], v[192:195], v[28:31]
	v_mfma_f32_16x16x32_bf16 v[24:27], v[142:145], v[182:185], v[24:27]
	v_mfma_f32_16x16x32_bf16 v[24:27], v[146:149], v[192:195], v[24:27]
	v_mfma_f32_16x16x32_bf16 v[8:11], v[142:145], v[196:199], v[8:11]
	v_mfma_f32_16x16x32_bf16 v[8:11], v[146:149], v[200:203], v[8:11]
	v_mfma_f32_16x16x32_bf16 v[12:15], v[134:137], v[196:199], v[12:15]
	v_mfma_f32_16x16x32_bf16 v[12:15], v[138:141], v[200:203], v[12:15]
	s_setprio 0
	s_setprio 1
	s_waitcnt lgkmcnt(0)
	v_mfma_f32_16x16x32_bf16 v[52:55], v[150:153], v[166:169], v[52:55]
	v_mfma_f32_16x16x32_bf16 v[52:55], v[154:157], v[170:173], v[52:55]
	v_mfma_f32_16x16x32_bf16 v[48:51], v[158:161], v[166:169], v[48:51]
	v_mfma_f32_16x16x32_bf16 v[48:51], v[162:165], v[170:173], v[48:51]
	v_mfma_f32_16x16x32_bf16 v[32:35], v[158:161], v[174:177], v[32:35]
	v_mfma_f32_16x16x32_bf16 v[32:35], v[162:165], v[178:181], v[32:35]
	v_mfma_f32_16x16x32_bf16 v[36:39], v[150:153], v[174:177], v[36:39]
	v_mfma_f32_16x16x32_bf16 v[36:39], v[154:157], v[178:181], v[36:39]
	v_mfma_f32_16x16x32_bf16 v[20:23], v[150:153], v[182:185], v[20:23]
	v_mfma_f32_16x16x32_bf16 v[20:23], v[154:157], v[192:195], v[20:23]
	v_mfma_f32_16x16x32_bf16 v[16:19], v[158:161], v[182:185], v[16:19]
	v_mfma_f32_16x16x32_bf16 v[16:19], v[162:165], v[192:195], v[16:19]
	v_mfma_f32_16x16x32_bf16 v[0:3], v[158:161], v[196:199], v[0:3]
	v_mfma_f32_16x16x32_bf16 v[0:3], v[162:165], v[200:203], v[0:3]
	v_mfma_f32_16x16x32_bf16 v[4:7], v[150:153], v[196:199], v[4:7]
	v_mfma_f32_16x16x32_bf16 v[4:7], v[154:157], v[200:203], v[4:7]
	s_setprio 0
	s_barrier
	s_add_i32 s77, s77, 2
	s_add_u32 s75, s75, 0x10000
	s_addc_u32 s76, s76, 0
	s_cmp_gt_u32 s77, 9
	s_mov_b64 s[28:29], s[2:3]
	s_cbranch_scc0 .LBB0_1953
	v_mbcnt_lo_u32_b32 v128, -1, 0
	v_mbcnt_hi_u32_b32 v128, -1, v128
	s_add_u32 s19, s69, s19
	v_lshlrev_b32_e32 v128, 4, v128
	v_add_u32_e32 v129, s60, v128
	v_add_u32_e32 v128, s62, v128
	s_addc_u32 s17, s70, s17
	s_mov_b32 s23, -2
	v_add_u32_e32 v128, 0, v128
	v_add_u32_e32 v129, 0, v129
